# loop-edge (7.12 step 2): rescale-test chain v_max/v_mov hoisted above the last PV MFMA of each tile, s_nop pads dropped, in all three attention loops
# baseline (speedup 1.0000x reference)
; #define LAS __attribute__((address_space(3)))
; template <int DV, int PAR, bool KW = true, bool KL = true, bool VL = true>
; __device__ __forceinline__ void attn_iter_full(AttnState<DV>& S, int t, LAS unsigned char* lds) {
;     ...
; #pragma unroll
;     for (int i = 0; i < NS; ++i) {
;         if (i + PD < NS) fr[(i + PD) % (PD + 1)] = AT_FRAG(i + PD);
;         if (i == 3) {
;             if (KW) *(LAS u32x4*)(lds + AT_K0 + PAR * AT_KB + S.kl) = S.kreg;
;             LAS unsigned char* W = lds + AT_V0 + (PAR ^ 1) * AT_VB + S.vl; *(LAS u32x4*)W = S.vreg0; if (DV == 128) *(LAS u32x4*)(W + 64 * 144) = S.vreg1; }
;         if (i == 5) { if (KL) S.kreg = *(const u32x4*)(S.kg + (size_t)(t + 3) * 4096);
;             if (VL) { S.vreg0 = *(const u32x4*)(S.vg + (t + 2) * 64); if (DV == 128) S.vreg1 = *(const u32x4*)(S.vg + (size_t)64 * TK + (t + 2) * 64); } }
;         if (i < 8) { if (i & 1) sn1 = MFMA32(fr[i % (PD + 1)], S.qr[i >> 1], sn1); else sn0 = MFMA32(fr[i % (PD + 1)], S.qr[i >> 1], sn0); }
;         else { const int j = i - 8; S.o[j % NDB] = MFMA32(fr[i % (PD + 1)], __builtin_bit_cast(bf16x8, pw[j / NDB]), S.o[j % NDB]); }
; #pragma unroll
;         for (int u = 0; u < NU; ++u) {
;             if (u * NS / NU != i) continue;
;             if (u < 20) {
;                 const int q = u / 5, r = u % 5;
;                 if (r < 4) { const int e = 8 * q + 2 * r;
;                     if (e < 16) { C0[e] = fast_exp2(C0[e]); C0[e + 1] = fast_exp2(C0[e + 1]); }
;                     else { C1[e - 16] = fast_exp2(C1[e - 16]); C1[e - 15] = fast_exp2(C1[e - 15]); } }
;                 else { if (q < 2) { const int b0 = 8 * q; pw[q].x = pk2(C0[b0], C0[b0 + 1]); pw[q].y = pk2(C0[b0 + 2], C0[b0 + 3]); pw[q].z = pk2(C0[b0 + 4], C0[b0 + 5]); pw[q].w = pk2(C0[b0 + 6], C0[b0 + 7]); }
;                        else { const int b0 = 8 * (q - 2); pw[q].x = pk2(C1[b0], C1[b0 + 1]); pw[q].y = pk2(C1[b0 + 2], C1[b0 + 3]); pw[q].z = pk2(C1[b0 + 4], C1[b0 + 5]); pw[q].w = pk2(C1[b0 + 6], C1[b0 + 7]); } }
;             } else if (u == 20) { ssum = C0 + C1; }
;             else if (u == 21) { const f32x4 a = (f32x4){ssum[0], ssum[1], ssum[2], ssum[3]} + (f32x4){ssum[4], ssum[5], ssum[6], ssum[7]} + (f32x4){ssum[8], ssum[9], ssum[10], ssum[11]} + (f32x4){ssum[12], ssum[13], ssum[14], ssum[15]};
;                 S.lsum += (a[0] + a[1]) + (a[2] + a[3]); }
.LBB0_397:
	ds_read_b128 v[32:35], v169 offset:9216
	ds_read_b128 v[36:39], v169 offset:13824
	ds_read_b128 v[40:43], v169 offset:9248
	s_waitcnt lgkmcnt(2)
	v_mfma_f32_32x32x16_bf16 v[112:127], v[32:35], v[140:143], v[64:79]
	ds_read_b128 v[44:47], v169 offset:13856
	v_exp_f32_e32 v32, v82
	v_exp_f32_e32 v34, v80
	v_exp_f32_e32 v35, v81
	v_exp_f32_e32 v33, v83
	s_waitcnt lgkmcnt(2)
	v_mfma_f32_32x32x16_bf16 v[96:111], v[36:39], v[140:143], v[64:79]
	ds_read_b128 v[80:83], v169 offset:9280
	v_exp_f32_e32 v38, v84
	v_exp_f32_e32 v39, v85
	v_exp_f32_e32 v36, v86
	v_exp_f32_e32 v37, v87
	s_waitcnt lgkmcnt(2)
	v_mfma_f32_32x32x16_bf16 v[112:127], v[40:43], v[136:139], v[112:127]
	ds_read_b128 v[84:87], v169 offset:13888
	v_cvt_pk_bf16_f32 v40, v34, v35
	v_cvt_pk_bf16_f32 v41, v32, v33
	v_cvt_pk_bf16_f32 v42, v38, v39
	v_cvt_pk_bf16_f32 v43, v36, v37
	v_exp_f32_e32 v176, v88
	v_exp_f32_e32 v177, v89
	s_waitcnt lgkmcnt(2)
	v_mfma_f32_32x32x16_bf16 v[96:111], v[44:47], v[136:139], v[96:111]
	ds_read_b128 v[172:175], v169 offset:9312
	s_waitcnt vmcnt(0)
	ds_write_b128 v168, v[144:147]
	ds_write_b128 v168, v[148:151] offset:36864
	v_exp_f32_e32 v178, v90
	v_exp_f32_e32 v179, v91
	s_waitcnt lgkmcnt(4)
	v_mfma_f32_32x32x16_bf16 v[112:127], v[80:83], v[132:135], v[112:127]
	ds_read_b128 v[44:47], v169 offset:13920
	v_exp_f32_e32 v92, v92
	v_exp_f32_e32 v93, v93
	v_exp_f32_e32 v94, v94
	v_exp_f32_e32 v95, v95
	ds_read_b128 v[80:83], v167 offset:18432
	global_load_dwordx4 v[144:147], v[156:157], off
	global_load_dwordx4 v[148:151], v[158:159], off offset:256
	s_waitcnt lgkmcnt(5)
	v_mfma_f32_32x32x16_bf16 v[96:111], v[84:87], v[132:135], v[96:111]
	v_cvt_pk_bf16_f32 v84, v176, v177
	v_exp_f32_e32 v180, v48
	v_exp_f32_e32 v181, v49
	v_cvt_pk_bf16_f32 v85, v178, v179
	v_cvt_pk_bf16_f32 v86, v92, v93
	v_cvt_pk_bf16_f32 v87, v94, v95
	s_waitcnt lgkmcnt(4)
	v_mfma_f32_32x32x16_bf16 v[112:127], v[172:175], v[128:131], v[112:127]
	ds_read_b128 v[88:91], v167 offset:23040
	v_exp_f32_e32 v172, v50
	v_exp_f32_e32 v173, v51
	s_waitcnt lgkmcnt(2)
	v_mfma_f32_32x32x16_bf16 v[96:111], v[44:47], v[128:131], v[96:111]
	ds_read_b128 v[48:51], v167 offset:18464
	v_exp_f32_e32 v174, v52
	v_exp_f32_e32 v175, v53
	v_exp_f32_e32 v182, v54
	v_exp_f32_e32 v183, v55
	s_waitcnt lgkmcnt(2)
	v_mfma_f32_32x32x16_bf16 v[0:15], v[80:83], v[40:43], v[0:15]
	ds_read_b128 v[44:47], v167 offset:23072
	v_cvt_pk_bf16_f32 v52, v180, v181
	v_cvt_pk_bf16_f32 v53, v172, v173
	v_cvt_pk_bf16_f32 v54, v174, v175
	v_cvt_pk_bf16_f32 v55, v182, v183
	v_exp_f32_e32 v56, v56
	v_exp_f32_e32 v57, v57
	s_waitcnt lgkmcnt(2)
	v_mfma_f32_32x32x16_bf16 v[16:31], v[88:91], v[40:43], v[16:31]
	ds_read_b128 v[80:83], v167 offset:18496
	v_exp_f32_e32 v58, v58
	v_exp_f32_e32 v59, v59
	s_waitcnt lgkmcnt(2)
	v_mfma_f32_32x32x16_bf16 v[0:15], v[48:51], v[84:87], v[0:15]
	ds_read_b128 v[40:43], v167 offset:23104
	v_exp_f32_e32 v60, v60
	v_exp_f32_e32 v61, v61
	v_exp_f32_e32 v62, v62
	v_exp_f32_e32 v63, v63
	s_waitcnt lgkmcnt(2)
	v_mfma_f32_32x32x16_bf16 v[16:31], v[44:47], v[84:87], v[16:31]
	ds_read_b128 v[48:51], v167 offset:18528
	v_cvt_pk_bf16_f32 v44, v56, v57
	v_cvt_pk_bf16_f32 v45, v58, v59
	v_cvt_pk_bf16_f32 v46, v60, v61
	v_cvt_pk_bf16_f32 v47, v62, v63
	v_pk_add_f32 v[60:61], v[60:61], v[92:93]
	v_pk_add_f32 v[62:63], v[62:63], v[94:95]
	v_pk_add_f32 v[58:59], v[58:59], v[178:179]
	v_pk_add_f32 v[56:57], v[56:57], v[176:177]
	v_pk_add_f32 v[38:39], v[174:175], v[38:39]
	v_pk_add_f32 v[84:85], v[180:181], v[34:35]
	v_pk_add_f32 v[36:37], v[182:183], v[36:37]
	v_pk_add_f32 v[86:87], v[172:173], v[32:33]
	s_waitcnt lgkmcnt(2)
	v_mfma_f32_32x32x16_bf16 v[0:15], v[80:83], v[52:55], v[0:15]
	v_add_f32_e64 v36, v86, v36
	v_add_f32_e64 v37, v87, v37
	v_add_f32_e64 v38, v84, v38
	v_add_f32_e64 v39, v85, v39
	v_add_f32_e64 v36, v58, v36
	v_add_f32_e64 v37, v59, v37
	v_pk_add_f32 v[38:39], v[56:57], v[38:39]
	ds_read_b128 v[32:35], v167 offset:23136
	v_pk_add_f32 v[36:37], v[62:63], v[36:37]
	v_pk_add_f32 v[38:39], v[60:61], v[38:39]
	s_nop 0
	v_pk_mov_b32 v[56:57], v[38:39], v[36:37] op_sel:[1,0]
	v_mov_b32_e32 v39, v37
	v_pk_add_f32 v[36:37], v[56:57], v[38:39]
	s_nop 0
	v_add_f32_e32 v36, v36, v37
	v_add_f32_e32 v171, v171, v36
	s_waitcnt lgkmcnt(2)
	v_mfma_f32_32x32x16_bf16 v[16:31], v[40:43], v[52:55], v[16:31]
	v_max3_f32 v36, v112, v113, v96
	v_max3_f32 v37, v114, v115, v97
	v_max3_f32 v36, v36, v98, v99
	v_max3_f32 v37, v37, v118, v119
	v_max3_f32 v36, v36, v116, v117
	v_max3_f32 v37, v37, v102, v103
	v_max3_f32 v36, v36, v100, v101
	s_waitcnt lgkmcnt(1)
	v_mfma_f32_32x32x16_bf16 v[0:15], v[48:51], v[44:47], v[0:15]
	v_max3_f32 v36, v36, v120, v121
	v_max3_f32 v37, v37, v122, v123
	v_max3_f32 v36, v36, v104, v105
	v_max3_f32 v37, v37, v106, v107
	v_max3_f32 v36, v36, v124, v125
	v_max3_f32 v37, v37, v126, v127
	v_max3_f32 v36, v36, v108, v109
	v_max3_f32 v37, v37, v110, v111
	v_max_f32_e32 v36, v36, v37
	v_mov_b32_e32 v37, v36
	s_waitcnt lgkmcnt(0)
	v_mfma_f32_32x32x16_bf16 v[16:31], v[32:35], v[44:47], v[16:31]
	v_permlane32_swap_b32_e32 v36, v37
	v_max_f32_e32 v32, v36, v37
	v_cmp_lt_f32_e32 vcc, s3, v32
	s_cbranch_vccz .LBB0_399
; #define LAS __attribute__((address_space(3)))
; __device__ __forceinline__ float fast_exp2(float x) { return __builtin_amdgcn_exp2f(x); }
; #define MFMA32(a, b, c) __builtin_amdgcn_mfma_f32_32x32x16_bf16((a), (b), (c), 0, 0, 0)
; template <int DV, int PAR, bool KW = true, bool KL = true, bool VL = true>
; __device__ __forceinline__ void attn_iter_full(AttnState<DV>& S, int t, LAS unsigned char* lds) {
;     constexpr int NDB = DV / 32, NS = 8 + 4 * NDB, NU = 27;
;     const LAS unsigned char* BK = lds + AT_K0 + (PAR ^ 1) * AT_KB + S.koff;
;     const LAS unsigned char* BV = lds + AT_V0 + PAR * AT_VB + S.voff;
;     f32x16& C0 = PAR ? S.sd0 : S.sc0; f32x16& C1 = PAR ? S.sd1 : S.sc1; f32x16& sn0 = PAR ? S.sc0 : S.sd0; f32x16& sn1 = PAR ? S.sc1 : S.sd1;
;     sn0 = S.negm; sn1 = S.negm;
;     u32x4 pw[4]; float mxa = 0.f, mxb = 0.f, mx = 0.f; f32x16 ssum;
;     constexpr int PD = (DV == 64) ? 3 : 2; bf16x8 fr[PD + 1];
;     ...
; #pragma unroll
;     for (int i = 0; i < PD; ++i) fr[i] = AT_FRAG(i);
;     __builtin_amdgcn_sched_barrier(0);
; #pragma unroll
;     for (int i = 0; i < NS; ++i) {
;         if (i + PD < NS) fr[(i + PD) % (PD + 1)] = AT_FRAG(i + PD);
;         if (i == 3) {
;             if (KW) *(LAS u32x4*)(lds + AT_K0 + PAR * AT_KB + S.kl) = S.kreg;
;             LAS unsigned char* W = lds + AT_V0 + (PAR ^ 1) * AT_VB + S.vl; *(LAS u32x4*)W = S.vreg0; if (DV == 128) *(LAS u32x4*)(W + 64 * 144) = S.vreg1; }
;         if (i == 5) { if (KL) S.kreg = *(const u32x4*)(S.kg + (size_t)(t + 3) * 4096);
;             if (VL) { S.vreg0 = *(const u32x4*)(S.vg + (t + 2) * 64); if (DV == 128) S.vreg1 = *(const u32x4*)(S.vg + (size_t)64 * TK + (t + 2) * 64); } }
;         if (i < 8) { if (i & 1) sn1 = MFMA32(fr[i % (PD + 1)], S.qr[i >> 1], sn1); else sn0 = MFMA32(fr[i % (PD + 1)], S.qr[i >> 1], sn0); }
;         else { const int j = i - 8; S.o[j % NDB] = MFMA32(fr[i % (PD + 1)], __builtin_bit_cast(bf16x8, pw[j / NDB]), S.o[j % NDB]); }
;     ...
;     if (__any(mx > 8.0f)) {
;         const float dl = fmaxf(mx, 0.f), alpha = fast_exp2(-dl);
;         S.mrun += dl; S.lsum *= alpha;
; #pragma unroll
;         for (int i = 0; i < 16; ++i) { sn0[i] -= dl; sn1[i] -= dl; S.negm[i] = -S.mrun; }
; #pragma unroll
;         for (int d = 0; d < NDB; ++d)
; #pragma unroll
;             for (int i = 0; i < 16; ++i) S.o[d][i] *= alpha;
;     }
	v_max_f32_e32 v32, v32, v32
	v_max_f32_e32 v34, 0, v32
	v_exp_f32_e64 v36, -v34
	v_add_f32_e32 v170, v170, v34
	v_xor_b32_e32 v32, 0x80000000, v170
	v_pk_add_f32 v[112:113], v[112:113], v[34:35] op_sel_hi:[1,0] neg_lo:[0,1] neg_hi:[0,1]
	v_mul_f32_e32 v171, v171, v36
	v_pk_add_f32 v[96:97], v[96:97], v[34:35] op_sel_hi:[1,0] neg_lo:[0,1] neg_hi:[0,1]
	v_pk_add_f32 v[114:115], v[114:115], v[34:35] op_sel_hi:[1,0] neg_lo:[0,1] neg_hi:[0,1]
	v_pk_add_f32 v[98:99], v[98:99], v[34:35] op_sel_hi:[1,0] neg_lo:[0,1] neg_hi:[0,1]
	v_pk_add_f32 v[116:117], v[116:117], v[34:35] op_sel_hi:[1,0] neg_lo:[0,1] neg_hi:[0,1]
	v_pk_add_f32 v[100:101], v[100:101], v[34:35] op_sel_hi:[1,0] neg_lo:[0,1] neg_hi:[0,1]
	v_pk_add_f32 v[118:119], v[118:119], v[34:35] op_sel_hi:[1,0] neg_lo:[0,1] neg_hi:[0,1]
	v_pk_add_f32 v[102:103], v[102:103], v[34:35] op_sel_hi:[1,0] neg_lo:[0,1] neg_hi:[0,1]
	v_pk_add_f32 v[120:121], v[120:121], v[34:35] op_sel_hi:[1,0] neg_lo:[0,1] neg_hi:[0,1]
	v_pk_add_f32 v[104:105], v[104:105], v[34:35] op_sel_hi:[1,0] neg_lo:[0,1] neg_hi:[0,1]
	v_pk_add_f32 v[122:123], v[122:123], v[34:35] op_sel_hi:[1,0] neg_lo:[0,1] neg_hi:[0,1]
	v_pk_add_f32 v[106:107], v[106:107], v[34:35] op_sel_hi:[1,0] neg_lo:[0,1] neg_hi:[0,1]
	v_pk_add_f32 v[124:125], v[124:125], v[34:35] op_sel_hi:[1,0] neg_lo:[0,1] neg_hi:[0,1]
	v_pk_add_f32 v[108:109], v[108:109], v[34:35] op_sel_hi:[1,0] neg_lo:[0,1] neg_hi:[0,1]
	v_pk_add_f32 v[126:127], v[126:127], v[34:35] op_sel_hi:[1,0] neg_lo:[0,1] neg_hi:[0,1]
	v_pk_add_f32 v[110:111], v[110:111], v[34:35] op_sel_hi:[1,0] neg_lo:[0,1] neg_hi:[0,1]
	v_pk_mul_f32 v[14:15], v[14:15], v[36:37] op_sel_hi:[1,0]
	v_pk_mul_f32 v[12:13], v[12:13], v[36:37] op_sel_hi:[1,0]
	v_pk_mul_f32 v[10:11], v[10:11], v[36:37] op_sel_hi:[1,0]
	v_pk_mul_f32 v[8:9], v[8:9], v[36:37] op_sel_hi:[1,0]
	v_pk_mul_f32 v[6:7], v[6:7], v[36:37] op_sel_hi:[1,0]
	v_pk_mul_f32 v[4:5], v[4:5], v[36:37] op_sel_hi:[1,0]
	v_pk_mul_f32 v[2:3], v[2:3], v[36:37] op_sel_hi:[1,0]
	v_pk_mul_f32 v[0:1], v[0:1], v[36:37] op_sel_hi:[1,0]
	v_pk_mul_f32 v[30:31], v[30:31], v[36:37] op_sel_hi:[1,0]
	v_pk_mul_f32 v[28:29], v[28:29], v[36:37] op_sel_hi:[1,0]
	v_pk_mul_f32 v[26:27], v[26:27], v[36:37] op_sel_hi:[1,0]
	v_pk_mul_f32 v[24:25], v[24:25], v[36:37] op_sel_hi:[1,0]
	v_pk_mul_f32 v[22:23], v[22:23], v[36:37] op_sel_hi:[1,0]
	v_pk_mul_f32 v[20:21], v[20:21], v[36:37] op_sel_hi:[1,0]
	v_pk_mul_f32 v[18:19], v[18:19], v[36:37] op_sel_hi:[1,0]
	v_pk_mul_f32 v[16:17], v[16:17], v[36:37] op_sel_hi:[1,0]
	v_mov_b32_e32 v33, v32
	v_mov_b32_e32 v34, v32
	v_mov_b32_e32 v35, v32
	v_mov_b32_e32 v36, v32
	v_mov_b32_e32 v37, v32
	v_mov_b32_e32 v38, v32
	v_mov_b32_e32 v39, v32
	v_mov_b32_e32 v40, v32
	v_mov_b32_e32 v41, v32
	v_mov_b32_e32 v42, v32
	v_mov_b32_e32 v43, v32
	v_mov_b32_e32 v44, v32
	v_mov_b32_e32 v45, v32
	v_mov_b32_e32 v46, v32
	v_mov_b32_e32 v47, v32
	v_mov_b32_e32 v64, v32
	v_mov_b32_e32 v65, v32
	v_mov_b32_e32 v66, v32
	v_mov_b32_e32 v67, v32
	v_mov_b32_e32 v68, v32
	v_mov_b32_e32 v69, v32
	v_mov_b32_e32 v70, v32
	v_mov_b32_e32 v71, v32
	v_mov_b32_e32 v72, v32
	v_mov_b32_e32 v73, v32
	v_mov_b32_e32 v74, v32
	v_mov_b32_e32 v75, v32
	v_mov_b32_e32 v76, v32
	v_mov_b32_e32 v77, v32
	v_mov_b32_e32 v78, v32
	v_mov_b32_e32 v79, v32
	s_branch .LBB0_400
.LBB0_399:
.LBB0_400:
	s_barrier
	ds_read_b128 v[48:51], v169
	ds_read_b128 v[172:175], v169 offset:4608
	ds_read_b128 v[176:179], v169 offset:32
	s_waitcnt lgkmcnt(2)
	v_mfma_f32_32x32x16_bf16 v[80:95], v[48:51], v[140:143], v[64:79]
	ds_read_b128 v[180:183], v169 offset:4640
	v_exp_f32_e32 v184, v112
	v_exp_f32_e32 v185, v113
	v_exp_f32_e32 v186, v114
	v_exp_f32_e32 v187, v115
	s_waitcnt lgkmcnt(2)
	v_mfma_f32_32x32x16_bf16 v[48:63], v[172:175], v[140:143], v[64:79]
	ds_read_b128 v[112:115], v169 offset:64
	v_exp_f32_e32 v188, v116
	v_exp_f32_e32 v189, v117
	v_exp_f32_e32 v190, v118
	v_exp_f32_e32 v191, v119
	s_waitcnt lgkmcnt(2)
	v_mfma_f32_32x32x16_bf16 v[80:95], v[176:179], v[136:139], v[80:95]
	ds_read_b128 v[116:119], v169 offset:4672
	v_cvt_pk_bf16_f32 v172, v184, v185
	v_cvt_pk_bf16_f32 v173, v186, v187
	v_cvt_pk_bf16_f32 v174, v188, v189
	v_cvt_pk_bf16_f32 v175, v190, v191
	v_exp_f32_e32 v192, v120
	v_exp_f32_e32 v193, v121
	s_waitcnt lgkmcnt(2)
	v_mfma_f32_32x32x16_bf16 v[48:63], v[180:183], v[136:139], v[48:63]
	ds_read_b128 v[176:179], v169 offset:96
	s_waitcnt vmcnt(0)
	ds_write_b128 v168, v[144:147] offset:9216
	ds_write_b128 v168, v[148:151] offset:18432
	v_exp_f32_e32 v196, v122
	v_exp_f32_e32 v197, v123
	s_waitcnt lgkmcnt(4)
	v_mfma_f32_32x32x16_bf16 v[80:95], v[112:115], v[132:135], v[80:95]
	ds_read_b128 v[120:123], v169 offset:4704
	v_exp_f32_e32 v180, v124
	v_exp_f32_e32 v181, v125
	v_exp_f32_e32 v182, v126
	v_exp_f32_e32 v183, v127
	v_lshl_add_u64 v[124:125], v[156:157], 0, s[100:101]
	ds_read_b128 v[112:115], v167 offset:36864
	global_load_dwordx4 v[144:147], v[124:125], off
	global_load_dwordx4 v[148:151], v[158:159], off offset:384
	s_waitcnt lgkmcnt(5)
	v_mfma_f32_32x32x16_bf16 v[48:63], v[116:119], v[132:135], v[48:63]
	v_cvt_pk_bf16_f32 v116, v192, v193
	v_exp_f32_e32 v162, v96
	v_exp_f32_e32 v163, v97
	v_cvt_pk_bf16_f32 v117, v196, v197
	v_cvt_pk_bf16_f32 v118, v180, v181
	v_cvt_pk_bf16_f32 v119, v182, v183
	s_waitcnt lgkmcnt(4)
	v_mfma_f32_32x32x16_bf16 v[80:95], v[176:179], v[128:131], v[80:95]
	ds_read_b128 v[124:127], v167 offset:41472
	v_exp_f32_e32 v164, v98
	v_exp_f32_e32 v165, v99
	s_waitcnt lgkmcnt(2)
	v_mfma_f32_32x32x16_bf16 v[48:63], v[120:123], v[128:131], v[48:63]
	ds_read_b128 v[96:99], v167 offset:36896
	v_exp_f32_e32 v176, v100
	v_exp_f32_e32 v177, v101
	v_exp_f32_e32 v178, v102
	v_exp_f32_e32 v179, v103
	s_waitcnt lgkmcnt(2)
; #define LAS __attribute__((address_space(3)))
; template <int DV, int PAR, bool KW = true, bool KL = true, bool VL = true>
; __device__ __forceinline__ void attn_iter_full(AttnState<DV>& S, int t, LAS unsigned char* lds) {
;     ...
;     for (int i = 0; i < NS; ++i) {
;         if (i + PD < NS) fr[(i + PD) % (PD + 1)] = AT_FRAG(i + PD);
;         if (i == 3) {
;             if (KW) *(LAS u32x4*)(lds + AT_K0 + PAR * AT_KB + S.kl) = S.kreg;
;             LAS unsigned char* W = lds + AT_V0 + (PAR ^ 1) * AT_VB + S.vl; *(LAS u32x4*)W = S.vreg0; if (DV == 128) *(LAS u32x4*)(W + 64 * 144) = S.vreg1; }
;         if (i == 5) { if (KL) S.kreg = *(const u32x4*)(S.kg + (size_t)(t + 3) * 4096);
;             if (VL) { S.vreg0 = *(const u32x4*)(S.vg + (t + 2) * 64); if (DV == 128) S.vreg1 = *(const u32x4*)(S.vg + (size_t)64 * TK + (t + 2) * 64); } }
;         if (i < 8) { if (i & 1) sn1 = MFMA32(fr[i % (PD + 1)], S.qr[i >> 1], sn1); else sn0 = MFMA32(fr[i % (PD + 1)], S.qr[i >> 1], sn0); }
;         else { const int j = i - 8; S.o[j % NDB] = MFMA32(fr[i % (PD + 1)], __builtin_bit_cast(bf16x8, pw[j / NDB]), S.o[j % NDB]); }
; #pragma unroll
;         for (int u = 0; u < NU; ++u) {
;             if (u * NS / NU != i) continue;
;             if (u < 20) {
;                 const int q = u / 5, r = u % 5;
;                 if (r < 4) { const int e = 8 * q + 2 * r;
;                     if (e < 16) { C0[e] = fast_exp2(C0[e]); C0[e + 1] = fast_exp2(C0[e + 1]); }
;                     else { C1[e - 16] = fast_exp2(C1[e - 16]); C1[e - 15] = fast_exp2(C1[e - 15]); } }
;                 else { if (q < 2) { const int b0 = 8 * q; pw[q].x = pk2(C0[b0], C0[b0 + 1]); pw[q].y = pk2(C0[b0 + 2], C0[b0 + 3]); pw[q].z = pk2(C0[b0 + 4], C0[b0 + 5]); pw[q].w = pk2(C0[b0 + 6], C0[b0 + 7]); }
;                        else { const int b0 = 8 * (q - 2); pw[q].x = pk2(C1[b0], C1[b0 + 1]); pw[q].y = pk2(C1[b0 + 2], C1[b0 + 3]); pw[q].z = pk2(C1[b0 + 4], C1[b0 + 5]); pw[q].w = pk2(C1[b0 + 6], C1[b0 + 7]); } }
;             } else if (u == 20) { ssum = C0 + C1; }
;             else if (u == 21) { const f32x4 a = (f32x4){ssum[0], ssum[1], ssum[2], ssum[3]} + (f32x4){ssum[4], ssum[5], ssum[6], ssum[7]} + (f32x4){ssum[8], ssum[9], ssum[10], ssum[11]} + (f32x4){ssum[12], ssum[13], ssum[14], ssum[15]};
;                 S.lsum += (a[0] + a[1]) + (a[2] + a[3]); }
	v_mfma_f32_32x32x16_bf16 v[0:15], v[112:115], v[172:175], v[0:15]
	ds_read_b128 v[100:103], v167 offset:41504
	v_cvt_pk_bf16_f32 v112, v162, v163
	v_cvt_pk_bf16_f32 v113, v164, v165
	v_cvt_pk_bf16_f32 v114, v176, v177
	v_cvt_pk_bf16_f32 v115, v178, v179
	v_exp_f32_e32 v198, v104
	v_exp_f32_e32 v199, v105
	s_waitcnt lgkmcnt(2)
	v_mfma_f32_32x32x16_bf16 v[16:31], v[124:127], v[172:175], v[16:31]
	ds_read_b128 v[120:123], v167 offset:36928
	v_exp_f32_e32 v124, v106
	v_exp_f32_e32 v125, v107
	s_waitcnt lgkmcnt(2)
	v_mfma_f32_32x32x16_bf16 v[0:15], v[96:99], v[116:119], v[0:15]
	ds_read_b128 v[104:107], v167 offset:41536
	v_exp_f32_e32 v108, v108
	v_exp_f32_e32 v109, v109
	v_exp_f32_e32 v110, v110
	v_exp_f32_e32 v111, v111
	s_waitcnt lgkmcnt(2)
	v_mfma_f32_32x32x16_bf16 v[16:31], v[100:103], v[116:119], v[16:31]
	ds_read_b128 v[96:99], v167 offset:36960
	v_cvt_pk_bf16_f32 v100, v198, v199
	v_cvt_pk_bf16_f32 v101, v124, v125
	v_cvt_pk_bf16_f32 v102, v108, v109
	v_cvt_pk_bf16_f32 v103, v110, v111
	v_pk_add_f32 v[116:117], v[108:109], v[180:181]
	v_pk_add_f32 v[118:119], v[110:111], v[182:183]
	v_pk_add_f32 v[124:125], v[124:125], v[196:197]
	v_pk_add_f32 v[126:127], v[198:199], v[192:193]
	v_pk_add_f32 v[172:173], v[176:177], v[188:189]
	v_pk_add_f32 v[162:163], v[162:163], v[184:185]
	v_pk_add_f32 v[174:175], v[178:179], v[190:191]
	v_pk_add_f32 v[164:165], v[164:165], v[186:187]
	s_waitcnt lgkmcnt(2)
	v_mfma_f32_32x32x16_bf16 v[0:15], v[120:123], v[112:115], v[0:15]
	v_add_f32_e64 v120, v164, v174
	v_add_f32_e64 v121, v165, v175
	v_add_f32_e64 v122, v162, v172
	v_add_f32_e64 v123, v163, v173
	v_add_f32_e64 v120, v124, v120
	v_add_f32_e64 v121, v125, v121
	v_pk_add_f32 v[122:123], v[126:127], v[122:123]
	v_pk_add_f32 v[118:119], v[118:119], v[120:121]
	v_pk_add_f32 v[116:117], v[116:117], v[122:123]
	ds_read_b128 v[108:111], v167 offset:41568
	v_pk_mov_b32 v[120:121], v[116:117], v[118:119] op_sel:[1,0]
	v_mov_b32_e32 v117, v119
	v_pk_add_f32 v[116:117], v[120:121], v[116:117]
	s_nop 0
	v_add_f32_e32 v116, v116, v117
	v_add_f32_e32 v171, v171, v116
	s_waitcnt lgkmcnt(2)
	v_mfma_f32_32x32x16_bf16 v[16:31], v[104:107], v[112:115], v[16:31]
	v_max3_f32 v104, v80, v81, v48
	v_max3_f32 v105, v82, v83, v49
	v_max3_f32 v104, v104, v50, v51
	v_max3_f32 v105, v105, v86, v87
	v_max3_f32 v104, v104, v84, v85
	v_max3_f32 v105, v105, v54, v55
	v_max3_f32 v104, v104, v52, v53
	s_waitcnt lgkmcnt(1)
	v_mfma_f32_32x32x16_bf16 v[0:15], v[96:99], v[100:103], v[0:15]
	v_max3_f32 v96, v104, v88, v89
	v_max3_f32 v97, v105, v90, v91
	v_max3_f32 v96, v96, v56, v57
	v_max3_f32 v97, v97, v58, v59
	v_max3_f32 v96, v96, v92, v93
	v_max3_f32 v97, v97, v94, v95
	v_max3_f32 v96, v96, v60, v61
	v_max3_f32 v97, v97, v62, v63
	v_max_f32_e32 v96, v96, v97
	v_mov_b32_e32 v97, v96
	s_waitcnt lgkmcnt(0)
	v_mfma_f32_32x32x16_bf16 v[16:31], v[108:111], v[100:103], v[16:31]
	v_permlane32_swap_b32_e32 v96, v97
	v_max_f32_e32 v96, v96, v97
	v_cmp_lt_f32_e32 vcc, s3, v96
	s_cbranch_vccz .LBB0_396
	v_max_f32_e32 v32, v96, v96
	v_max_f32_e32 v33, 0, v32
	v_exp_f32_e64 v34, -v33
	v_add_f32_e32 v170, v170, v33
	v_xor_b32_e32 v32, 0x80000000, v170
	v_sub_f32_e32 v95, v95, v33
	v_mul_f32_e32 v171, v171, v34
	v_sub_f32_e32 v94, v94, v33
	v_sub_f32_e32 v93, v93, v33
	v_sub_f32_e32 v92, v92, v33
	v_sub_f32_e32 v91, v91, v33
	v_sub_f32_e32 v90, v90, v33
	v_sub_f32_e32 v89, v89, v33
	v_sub_f32_e32 v88, v88, v33
	v_sub_f32_e32 v87, v87, v33
	v_sub_f32_e32 v86, v86, v33
	v_sub_f32_e32 v85, v85, v33
	v_sub_f32_e32 v84, v84, v33
	v_sub_f32_e32 v83, v83, v33
	v_sub_f32_e32 v82, v82, v33
	v_sub_f32_e32 v81, v81, v33
	v_sub_f32_e32 v80, v80, v33
	v_sub_f32_e32 v63, v63, v33
	v_sub_f32_e32 v62, v62, v33
	v_sub_f32_e32 v61, v61, v33
	v_sub_f32_e32 v60, v60, v33
	v_sub_f32_e32 v59, v59, v33
	v_sub_f32_e32 v58, v58, v33
	v_sub_f32_e32 v57, v57, v33
	v_sub_f32_e32 v56, v56, v33
	v_sub_f32_e32 v55, v55, v33
	v_sub_f32_e32 v54, v54, v33
	v_sub_f32_e32 v53, v53, v33
	v_sub_f32_e32 v52, v52, v33
	v_sub_f32_e32 v51, v51, v33
	v_sub_f32_e32 v50, v50, v33
	v_sub_f32_e32 v49, v49, v33
	v_sub_f32_e32 v48, v48, v33
	v_pk_mul_f32 v[14:15], v[14:15], v[34:35] op_sel_hi:[1,0]
	v_pk_mul_f32 v[12:13], v[12:13], v[34:35] op_sel_hi:[1,0]
	v_pk_mul_f32 v[10:11], v[10:11], v[34:35] op_sel_hi:[1,0]
	v_pk_mul_f32 v[8:9], v[8:9], v[34:35] op_sel_hi:[1,0]
	v_pk_mul_f32 v[6:7], v[6:7], v[34:35] op_sel_hi:[1,0]
	v_pk_mul_f32 v[4:5], v[4:5], v[34:35] op_sel_hi:[1,0]
	v_pk_mul_f32 v[2:3], v[2:3], v[34:35] op_sel_hi:[1,0]
	v_pk_mul_f32 v[0:1], v[0:1], v[34:35] op_sel_hi:[1,0]
	v_pk_mul_f32 v[30:31], v[30:31], v[34:35] op_sel_hi:[1,0]
	v_pk_mul_f32 v[28:29], v[28:29], v[34:35] op_sel_hi:[1,0]
	v_pk_mul_f32 v[26:27], v[26:27], v[34:35] op_sel_hi:[1,0]
	v_pk_mul_f32 v[24:25], v[24:25], v[34:35] op_sel_hi:[1,0]
	v_pk_mul_f32 v[22:23], v[22:23], v[34:35] op_sel_hi:[1,0]
	v_pk_mul_f32 v[20:21], v[20:21], v[34:35] op_sel_hi:[1,0]
	v_pk_mul_f32 v[18:19], v[18:19], v[34:35] op_sel_hi:[1,0]
	v_pk_mul_f32 v[16:17], v[16:17], v[34:35] op_sel_hi:[1,0]
	v_mov_b32_e32 v33, v32
	v_mov_b32_e32 v34, v32
	v_mov_b32_e32 v35, v32
	v_mov_b32_e32 v36, v32
	v_mov_b32_e32 v37, v32
	v_mov_b32_e32 v38, v32
	v_mov_b32_e32 v39, v32
	v_mov_b32_e32 v40, v32
	v_mov_b32_e32 v41, v32
	v_mov_b32_e32 v42, v32
	v_mov_b32_e32 v43, v32
	v_mov_b32_e32 v44, v32
	v_mov_b32_e32 v45, v32
	v_mov_b32_e32 v46, v32
	v_mov_b32_e32 v47, v32
	v_mov_b32_e32 v64, v32
	v_mov_b32_e32 v65, v32
	v_mov_b32_e32 v66, v32
	v_mov_b32_e32 v67, v32
	v_mov_b32_e32 v68, v32
	v_mov_b32_e32 v69, v32
	v_mov_b32_e32 v70, v32
	v_mov_b32_e32 v71, v32
	v_mov_b32_e32 v72, v32
	v_mov_b32_e32 v73, v32
	v_mov_b32_e32 v74, v32
	v_mov_b32_e32 v75, v32
	v_mov_b32_e32 v76, v32
	v_mov_b32_e32 v77, v32
	v_mov_b32_e32 v78, v32
	v_mov_b32_e32 v79, v32
	s_branch .LBB0_396

; #define LAS __attribute__((address_space(3)))
; template <int DV, int PAR, bool KW = true, bool KL = true, bool VL = true>
; __device__ __forceinline__ void attn_iter_full(AttnState<DV>& S, int t, LAS unsigned char* lds) {
;     ...
; #pragma unroll
;     for (int i = 0; i < NS; ++i) {
;         if (i + PD < NS) fr[(i + PD) % (PD + 1)] = AT_FRAG(i + PD);
;         if (i == 3) {
;             if (KW) *(LAS u32x4*)(lds + AT_K0 + PAR * AT_KB + S.kl) = S.kreg;
;             LAS unsigned char* W = lds + AT_V0 + (PAR ^ 1) * AT_VB + S.vl; *(LAS u32x4*)W = S.vreg0; if (DV == 128) *(LAS u32x4*)(W + 64 * 144) = S.vreg1; }
;         if (i == 5) { if (KL) S.kreg = *(const u32x4*)(S.kg + (size_t)(t + 3) * 4096);
;             if (VL) { S.vreg0 = *(const u32x4*)(S.vg + (t + 2) * 64); if (DV == 128) S.vreg1 = *(const u32x4*)(S.vg + (size_t)64 * TK + (t + 2) * 64); } }
;         if (i < 8) { if (i & 1) sn1 = MFMA32(fr[i % (PD + 1)], S.qr[i >> 1], sn1); else sn0 = MFMA32(fr[i % (PD + 1)], S.qr[i >> 1], sn0); }
;         else { const int j = i - 8; S.o[j % NDB] = MFMA32(fr[i % (PD + 1)], __builtin_bit_cast(bf16x8, pw[j / NDB]), S.o[j % NDB]); }
; #pragma unroll
;         for (int u = 0; u < NU; ++u) {
;             if (u * NS / NU != i) continue;
;             if (u < 20) {
;                 const int q = u / 5, r = u % 5;
;                 if (r < 4) { const int e = 8 * q + 2 * r;
;                     if (e < 16) { C0[e] = fast_exp2(C0[e]); C0[e + 1] = fast_exp2(C0[e + 1]); }
;                     else { C1[e - 16] = fast_exp2(C1[e - 16]); C1[e - 15] = fast_exp2(C1[e - 15]); } }
;                 else { if (q < 2) { const int b0 = 8 * q; pw[q].x = pk2(C0[b0], C0[b0 + 1]); pw[q].y = pk2(C0[b0 + 2], C0[b0 + 3]); pw[q].z = pk2(C0[b0 + 4], C0[b0 + 5]); pw[q].w = pk2(C0[b0 + 6], C0[b0 + 7]); }
;                        else { const int b0 = 8 * (q - 2); pw[q].x = pk2(C1[b0], C1[b0 + 1]); pw[q].y = pk2(C1[b0 + 2], C1[b0 + 3]); pw[q].z = pk2(C1[b0 + 4], C1[b0 + 5]); pw[q].w = pk2(C1[b0 + 6], C1[b0 + 7]); } }
;             } else if (u == 20) { ssum = C0 + C1; }
;             else if (u == 21) { const f32x4 a = (f32x4){ssum[0], ssum[1], ssum[2], ssum[3]} + (f32x4){ssum[4], ssum[5], ssum[6], ssum[7]} + (f32x4){ssum[8], ssum[9], ssum[10], ssum[11]} + (f32x4){ssum[12], ssum[13], ssum[14], ssum[15]};
;                 S.lsum += (a[0] + a[1]) + (a[2] + a[3]); }
.LBB0_414:
	ds_read_b128 v[64:67], v231 offset:9216
	ds_read_b128 v[68:71], v231 offset:13824
	s_waitcnt lgkmcnt(1)
	v_mfma_f32_32x32x16_bf16 v[144:159], v[64:67], v[174:177], v[96:111]
	ds_read_b128 v[72:75], v231 offset:9248
	v_exp_f32_e32 v64, v114
	v_exp_f32_e32 v66, v112
	v_exp_f32_e32 v67, v113
	v_exp_f32_e32 v65, v115
	s_waitcnt lgkmcnt(1)
	v_mfma_f32_32x32x16_bf16 v[128:143], v[68:71], v[174:177], v[96:111]
	ds_read_b128 v[76:79], v231 offset:13856
	v_exp_f32_e32 v68, v116
	v_exp_f32_e32 v69, v117
	s_waitcnt lgkmcnt(1)
	v_mfma_f32_32x32x16_bf16 v[144:159], v[72:75], v[170:173], v[144:159]
	ds_read_b128 v[112:115], v231 offset:9280
	v_exp_f32_e32 v70, v118
	v_exp_f32_e32 v71, v119
	s_waitcnt lgkmcnt(1)
	v_mfma_f32_32x32x16_bf16 v[128:143], v[76:79], v[170:173], v[128:143]
	ds_read_b128 v[116:119], v231 offset:13888
	s_waitcnt vmcnt(0)
	ds_write_b128 v232, v[178:181]
	ds_write_b128 v232, v[182:185] offset:36864
	ds_write_b128 v232, v[186:189] offset:46080
	v_cvt_pk_bf16_f32 v74, v66, v67
	v_cvt_pk_bf16_f32 v75, v64, v65
	v_cvt_pk_bf16_f32 v76, v68, v69
	v_cvt_pk_bf16_f32 v77, v70, v71
	s_waitcnt lgkmcnt(4)
	v_mfma_f32_32x32x16_bf16 v[144:159], v[112:115], v[166:169], v[144:159]
	ds_read_b128 v[234:237], v231 offset:9312
	v_exp_f32_e32 v72, v120
	v_exp_f32_e32 v73, v121
	ds_read_b128 v[112:115], v231 offset:13920
	global_load_dwordx4 v[178:181], v[206:207], off
	global_load_dwordx4 v[182:185], v[208:209], off offset:256
	v_lshl_add_u64 v[214:215], v[208:209], 0, s[16:17]
	global_load_dwordx4 v[186:189], v[214:215], off offset:256
	s_waitcnt lgkmcnt(5)
	v_mfma_f32_32x32x16_bf16 v[128:143], v[116:119], v[166:169], v[128:143]
	v_exp_f32_e32 v190, v122
	v_exp_f32_e32 v191, v123
	s_waitcnt lgkmcnt(1)
	v_mfma_f32_32x32x16_bf16 v[144:159], v[234:237], v[162:165], v[144:159]
	ds_read_b128 v[116:119], v230 offset:18432
	v_exp_f32_e32 v124, v124
	v_exp_f32_e32 v125, v125
	s_waitcnt lgkmcnt(1)
	v_mfma_f32_32x32x16_bf16 v[128:143], v[112:115], v[162:165], v[128:143]
	ds_read_b128 v[120:123], v230 offset:23040
	v_exp_f32_e32 v126, v126
	v_exp_f32_e32 v127, v127
	s_waitcnt lgkmcnt(1)
	v_mfma_f32_32x32x16_bf16 v[48:63], v[116:119], v[74:77], v[48:63]
	ds_read_b128 v[112:115], v230 offset:27648
	v_cvt_pk_bf16_f32 v116, v72, v73
	v_cvt_pk_bf16_f32 v117, v190, v191
	v_cvt_pk_bf16_f32 v118, v124, v125
	v_cvt_pk_bf16_f32 v119, v126, v127
	v_exp_f32_e32 v192, v80
	v_exp_f32_e32 v193, v81
	s_waitcnt lgkmcnt(1)
	v_mfma_f32_32x32x16_bf16 v[32:47], v[120:123], v[74:77], v[32:47]
	ds_read_b128 v[78:81], v230 offset:32256
	v_exp_f32_e32 v196, v82
	v_exp_f32_e32 v197, v83
	s_waitcnt lgkmcnt(1)
	v_mfma_f32_32x32x16_bf16 v[16:31], v[112:115], v[74:77], v[16:31]
	ds_read_b128 v[120:123], v230 offset:18464
	v_exp_f32_e32 v198, v84
	v_exp_f32_e32 v199, v85
	s_waitcnt lgkmcnt(1)
	v_mfma_f32_32x32x16_bf16 v[0:15], v[78:81], v[74:77], v[0:15]
	ds_read_b128 v[82:85], v230 offset:23072
	v_exp_f32_e32 v234, v86
	v_exp_f32_e32 v235, v87
	s_waitcnt lgkmcnt(1)
	v_mfma_f32_32x32x16_bf16 v[48:63], v[120:123], v[116:119], v[48:63]
	ds_read_b128 v[74:77], v230 offset:27680
	v_cvt_pk_bf16_f32 v78, v192, v193
	v_cvt_pk_bf16_f32 v79, v196, v197
	v_cvt_pk_bf16_f32 v80, v198, v199
	v_cvt_pk_bf16_f32 v81, v234, v235
	s_waitcnt lgkmcnt(1)
	v_mfma_f32_32x32x16_bf16 v[32:47], v[82:85], v[116:119], v[32:47]
	ds_read_b128 v[112:115], v230 offset:32288
	v_exp_f32_e32 v120, v88
	v_exp_f32_e32 v121, v89
	s_waitcnt lgkmcnt(1)
	v_mfma_f32_32x32x16_bf16 v[16:31], v[74:77], v[116:119], v[16:31]
	ds_read_b128 v[82:85], v230 offset:18496
	v_exp_f32_e32 v122, v90
	v_exp_f32_e32 v123, v91
	s_waitcnt lgkmcnt(1)
	v_mfma_f32_32x32x16_bf16 v[0:15], v[112:115], v[116:119], v[0:15]
	ds_read_b128 v[74:77], v230 offset:23104
	v_exp_f32_e32 v112, v92
	v_exp_f32_e32 v113, v93
	s_waitcnt lgkmcnt(1)
	v_mfma_f32_32x32x16_bf16 v[48:63], v[82:85], v[78:81], v[48:63]
	ds_read_b128 v[86:89], v230 offset:27712
	v_exp_f32_e32 v94, v94
	v_exp_f32_e32 v95, v95
	v_cvt_pk_bf16_f32 v82, v120, v121
	v_cvt_pk_bf16_f32 v83, v122, v123
	v_cvt_pk_bf16_f32 v84, v112, v113
	v_cvt_pk_bf16_f32 v85, v94, v95
	s_waitcnt lgkmcnt(1)
	v_mfma_f32_32x32x16_bf16 v[32:47], v[74:77], v[78:81], v[32:47]
	ds_read_b128 v[90:93], v230 offset:32320
	v_add_f32_e64 v74, v112, v124
	v_add_f32_e64 v75, v113, v125
	v_add_f32_e64 v76, v94, v126
	v_add_f32_e64 v77, v95, v127
	v_pk_add_f32 v[94:95], v[122:123], v[190:191]
	v_pk_add_f32 v[72:73], v[120:121], v[72:73]
	v_pk_add_f32 v[68:69], v[198:199], v[68:69]
	v_pk_add_f32 v[112:113], v[192:193], v[66:67]
	v_pk_add_f32 v[70:71], v[234:235], v[70:71]
	v_pk_add_f32 v[114:115], v[196:197], v[64:65]
	s_waitcnt lgkmcnt(1)
	v_mfma_f32_32x32x16_bf16 v[16:31], v[86:89], v[78:81], v[16:31]
	v_add_f32_e64 v70, v114, v70
	v_add_f32_e64 v71, v115, v71
	v_add_f32_e64 v68, v112, v68
	v_add_f32_e64 v69, v113, v69
	v_add_f32_e64 v70, v94, v70
	v_add_f32_e64 v71, v95, v71
	v_pk_add_f32 v[68:69], v[72:73], v[68:69]
	ds_read_b128 v[64:67], v230 offset:18528
	v_pk_add_f32 v[70:71], v[76:77], v[70:71]
	v_pk_add_f32 v[68:69], v[74:75], v[68:69]
	s_nop 0
	v_pk_mov_b32 v[72:73], v[68:69], v[70:71] op_sel:[1,0]
	v_mov_b32_e32 v69, v71
	v_pk_add_f32 v[68:69], v[72:73], v[68:69]
	s_nop 0
	v_add_f32_e32 v68, v68, v69
	v_add_f32_e32 v234, v216, v68
	s_waitcnt lgkmcnt(1)
	v_mfma_f32_32x32x16_bf16 v[0:15], v[90:93], v[78:81], v[0:15]
	ds_read_b128 v[68:71], v230 offset:23136
	v_max3_f32 v72, v144, v145, v128
	v_max3_f32 v76, v146, v147, v129
	v_max3_f32 v77, v72, v130, v131
	s_waitcnt lgkmcnt(1)
	v_mfma_f32_32x32x16_bf16 v[48:63], v[64:67], v[82:85], v[48:63]
	ds_read_b128 v[72:75], v230 offset:27744
	v_max3_f32 v64, v77, v148, v149
	v_max3_f32 v65, v76, v150, v151
	v_max3_f32 v76, v64, v132, v133
	v_max3_f32 v77, v65, v134, v135
	s_waitcnt lgkmcnt(1)
	v_mfma_f32_32x32x16_bf16 v[32:47], v[68:71], v[82:85], v[32:47]
	ds_read_b128 v[64:67], v230 offset:32352
	v_max3_f32 v68, v76, v152, v153
	v_max3_f32 v69, v77, v154, v155
	v_max3_f32 v68, v68, v136, v137
	v_max3_f32 v69, v69, v138, v139
	s_waitcnt lgkmcnt(1)
	v_mfma_f32_32x32x16_bf16 v[16:31], v[72:75], v[82:85], v[16:31]
	v_max3_f32 v68, v68, v156, v157
	v_max3_f32 v69, v69, v158, v159
	v_max3_f32 v68, v68, v140, v141
	v_max3_f32 v69, v69, v142, v143
	v_max_f32_e32 v68, v68, v69
	v_mov_b32_e32 v69, v68
	s_waitcnt lgkmcnt(0)
	v_mfma_f32_32x32x16_bf16 v[0:15], v[64:67], v[82:85], v[0:15]
	v_permlane32_swap_b32_e32 v68, v69
	v_max_f32_e32 v64, v68, v69
	v_cmp_lt_f32_e32 vcc, s3, v64
	s_cbranch_vccz .LBB0_416
; __device__ __forceinline__ float fast_exp2(float x) { return __builtin_amdgcn_exp2f(x); }
; template <int DV, int PAR, bool KW = true, bool KL = true, bool VL = true>
; __device__ __forceinline__ void attn_iter_full(AttnState<DV>& S, int t, LAS unsigned char* lds) {
;     ...
;     if (__any(mx > 8.0f)) {
;         const float dl = fmaxf(mx, 0.f), alpha = fast_exp2(-dl);
;         S.mrun += dl; S.lsum *= alpha;
; #pragma unroll
;         for (int i = 0; i < 16; ++i) { sn0[i] -= dl; sn1[i] -= dl; S.negm[i] = -S.mrun; }
; #pragma unroll
;         for (int d = 0; d < NDB; ++d)
; #pragma unroll
;             for (int i = 0; i < 16; ++i) S.o[d][i] *= alpha;
;     }
	v_max_f32_e32 v64, v64, v64
	v_max_f32_e32 v66, 0, v64
	v_exp_f32_e64 v68, -v66
	v_add_f32_e32 v233, v233, v66
	v_xor_b32_e32 v64, 0x80000000, v233
	v_pk_add_f32 v[144:145], v[144:145], v[66:67] op_sel_hi:[1,0] neg_lo:[0,1] neg_hi:[0,1]
	v_mul_f32_e32 v234, v234, v68
	v_pk_add_f32 v[128:129], v[128:129], v[66:67] op_sel_hi:[1,0] neg_lo:[0,1] neg_hi:[0,1]
	v_pk_add_f32 v[146:147], v[146:147], v[66:67] op_sel_hi:[1,0] neg_lo:[0,1] neg_hi:[0,1]
	v_pk_add_f32 v[130:131], v[130:131], v[66:67] op_sel_hi:[1,0] neg_lo:[0,1] neg_hi:[0,1]
	v_pk_add_f32 v[148:149], v[148:149], v[66:67] op_sel_hi:[1,0] neg_lo:[0,1] neg_hi:[0,1]
	v_pk_add_f32 v[132:133], v[132:133], v[66:67] op_sel_hi:[1,0] neg_lo:[0,1] neg_hi:[0,1]
	v_pk_add_f32 v[150:151], v[150:151], v[66:67] op_sel_hi:[1,0] neg_lo:[0,1] neg_hi:[0,1]
	v_pk_add_f32 v[134:135], v[134:135], v[66:67] op_sel_hi:[1,0] neg_lo:[0,1] neg_hi:[0,1]
	v_pk_add_f32 v[152:153], v[152:153], v[66:67] op_sel_hi:[1,0] neg_lo:[0,1] neg_hi:[0,1]
	v_pk_add_f32 v[136:137], v[136:137], v[66:67] op_sel_hi:[1,0] neg_lo:[0,1] neg_hi:[0,1]
	v_pk_add_f32 v[154:155], v[154:155], v[66:67] op_sel_hi:[1,0] neg_lo:[0,1] neg_hi:[0,1]
	v_pk_add_f32 v[138:139], v[138:139], v[66:67] op_sel_hi:[1,0] neg_lo:[0,1] neg_hi:[0,1]
	v_pk_add_f32 v[156:157], v[156:157], v[66:67] op_sel_hi:[1,0] neg_lo:[0,1] neg_hi:[0,1]
	v_pk_add_f32 v[140:141], v[140:141], v[66:67] op_sel_hi:[1,0] neg_lo:[0,1] neg_hi:[0,1]
	v_pk_add_f32 v[158:159], v[158:159], v[66:67] op_sel_hi:[1,0] neg_lo:[0,1] neg_hi:[0,1]
	v_pk_add_f32 v[142:143], v[142:143], v[66:67] op_sel_hi:[1,0] neg_lo:[0,1] neg_hi:[0,1]
	v_pk_mul_f32 v[62:63], v[62:63], v[68:69] op_sel_hi:[1,0]
	v_pk_mul_f32 v[60:61], v[60:61], v[68:69] op_sel_hi:[1,0]
	v_pk_mul_f32 v[58:59], v[58:59], v[68:69] op_sel_hi:[1,0]
	v_pk_mul_f32 v[56:57], v[56:57], v[68:69] op_sel_hi:[1,0]
	v_pk_mul_f32 v[54:55], v[54:55], v[68:69] op_sel_hi:[1,0]
	v_pk_mul_f32 v[52:53], v[52:53], v[68:69] op_sel_hi:[1,0]
	v_pk_mul_f32 v[50:51], v[50:51], v[68:69] op_sel_hi:[1,0]
	v_pk_mul_f32 v[48:49], v[48:49], v[68:69] op_sel_hi:[1,0]
	v_pk_mul_f32 v[46:47], v[46:47], v[68:69] op_sel_hi:[1,0]
	v_pk_mul_f32 v[44:45], v[44:45], v[68:69] op_sel_hi:[1,0]
	v_pk_mul_f32 v[42:43], v[42:43], v[68:69] op_sel_hi:[1,0]
	v_pk_mul_f32 v[40:41], v[40:41], v[68:69] op_sel_hi:[1,0]
	v_pk_mul_f32 v[38:39], v[38:39], v[68:69] op_sel_hi:[1,0]
	v_pk_mul_f32 v[36:37], v[36:37], v[68:69] op_sel_hi:[1,0]
	v_pk_mul_f32 v[34:35], v[34:35], v[68:69] op_sel_hi:[1,0]
	v_pk_mul_f32 v[32:33], v[32:33], v[68:69] op_sel_hi:[1,0]
	v_pk_mul_f32 v[30:31], v[30:31], v[68:69] op_sel_hi:[1,0]
	v_pk_mul_f32 v[28:29], v[28:29], v[68:69] op_sel_hi:[1,0]
	v_pk_mul_f32 v[26:27], v[26:27], v[68:69] op_sel_hi:[1,0]
	v_pk_mul_f32 v[24:25], v[24:25], v[68:69] op_sel_hi:[1,0]
	v_pk_mul_f32 v[22:23], v[22:23], v[68:69] op_sel_hi:[1,0]
	v_pk_mul_f32 v[20:21], v[20:21], v[68:69] op_sel_hi:[1,0]
	v_pk_mul_f32 v[18:19], v[18:19], v[68:69] op_sel_hi:[1,0]
	v_pk_mul_f32 v[16:17], v[16:17], v[68:69] op_sel_hi:[1,0]
	v_pk_mul_f32 v[14:15], v[14:15], v[68:69] op_sel_hi:[1,0]
	v_pk_mul_f32 v[12:13], v[12:13], v[68:69] op_sel_hi:[1,0]
	v_pk_mul_f32 v[10:11], v[10:11], v[68:69] op_sel_hi:[1,0]
	v_pk_mul_f32 v[8:9], v[8:9], v[68:69] op_sel_hi:[1,0]
	v_pk_mul_f32 v[6:7], v[6:7], v[68:69] op_sel_hi:[1,0]
	v_pk_mul_f32 v[4:5], v[4:5], v[68:69] op_sel_hi:[1,0]
	v_pk_mul_f32 v[2:3], v[2:3], v[68:69] op_sel_hi:[1,0]
	v_pk_mul_f32 v[0:1], v[0:1], v[68:69] op_sel_hi:[1,0]
	v_mov_b32_e32 v65, v64
	v_mov_b32_e32 v66, v64
	v_mov_b32_e32 v67, v64
	v_mov_b32_e32 v68, v64
	v_mov_b32_e32 v69, v64
	v_mov_b32_e32 v70, v64
	v_mov_b32_e32 v71, v64
	v_mov_b32_e32 v72, v64
	v_mov_b32_e32 v73, v64
	v_mov_b32_e32 v74, v64
	v_mov_b32_e32 v75, v64
	v_mov_b32_e32 v76, v64
	v_mov_b32_e32 v77, v64
	v_mov_b32_e32 v78, v64
	v_mov_b32_e32 v79, v64
	v_mov_b32_e32 v96, v64
	v_mov_b32_e32 v97, v64
	v_mov_b32_e32 v98, v64
	v_mov_b32_e32 v99, v64
	v_mov_b32_e32 v100, v64
	v_mov_b32_e32 v101, v64
	v_mov_b32_e32 v102, v64
	v_mov_b32_e32 v103, v64
	v_mov_b32_e32 v104, v64
	v_mov_b32_e32 v105, v64
	v_mov_b32_e32 v106, v64
	v_mov_b32_e32 v107, v64
	v_mov_b32_e32 v108, v64
	v_mov_b32_e32 v109, v64
	v_mov_b32_e32 v110, v64
	v_mov_b32_e32 v111, v64
	s_branch .LBB0_417
; #define LAS __attribute__((address_space(3)))
; template <int DV, int PAR, bool KW = true, bool KL = true, bool VL = true>
; __device__ __forceinline__ void attn_iter_full(AttnState<DV>& S, int t, LAS unsigned char* lds) {
;     ...
;     for (int i = 0; i < NS; ++i) {
;         if (i + PD < NS) fr[(i + PD) % (PD + 1)] = AT_FRAG(i + PD);
;         if (i == 3) {
;             if (KW) *(LAS u32x4*)(lds + AT_K0 + PAR * AT_KB + S.kl) = S.kreg;
;             LAS unsigned char* W = lds + AT_V0 + (PAR ^ 1) * AT_VB + S.vl; *(LAS u32x4*)W = S.vreg0; if (DV == 128) *(LAS u32x4*)(W + 64 * 144) = S.vreg1; }
;         if (i == 5) { if (KL) S.kreg = *(const u32x4*)(S.kg + (size_t)(t + 3) * 4096);
;             if (VL) { S.vreg0 = *(const u32x4*)(S.vg + (t + 2) * 64); if (DV == 128) S.vreg1 = *(const u32x4*)(S.vg + (size_t)64 * TK + (t + 2) * 64); } }
;         if (i < 8) { if (i & 1) sn1 = MFMA32(fr[i % (PD + 1)], S.qr[i >> 1], sn1); else sn0 = MFMA32(fr[i % (PD + 1)], S.qr[i >> 1], sn0); }
;         else { const int j = i - 8; S.o[j % NDB] = MFMA32(fr[i % (PD + 1)], __builtin_bit_cast(bf16x8, pw[j / NDB]), S.o[j % NDB]); }
; #pragma unroll
;         for (int u = 0; u < NU; ++u) {
;             if (u * NS / NU != i) continue;
;             if (u < 20) {
;                 const int q = u / 5, r = u % 5;
;                 if (r < 4) { const int e = 8 * q + 2 * r;
;                     if (e < 16) { C0[e] = fast_exp2(C0[e]); C0[e + 1] = fast_exp2(C0[e + 1]); }
;                     else { C1[e - 16] = fast_exp2(C1[e - 16]); C1[e - 15] = fast_exp2(C1[e - 15]); } }
;                 else { if (q < 2) { const int b0 = 8 * q; pw[q].x = pk2(C0[b0], C0[b0 + 1]); pw[q].y = pk2(C0[b0 + 2], C0[b0 + 3]); pw[q].z = pk2(C0[b0 + 4], C0[b0 + 5]); pw[q].w = pk2(C0[b0 + 6], C0[b0 + 7]); }
;                        else { const int b0 = 8 * (q - 2); pw[q].x = pk2(C1[b0], C1[b0 + 1]); pw[q].y = pk2(C1[b0 + 2], C1[b0 + 3]); pw[q].z = pk2(C1[b0 + 4], C1[b0 + 5]); pw[q].w = pk2(C1[b0 + 6], C1[b0 + 7]); } }
;             } else if (u == 20) { ssum = C0 + C1; }
;             else if (u == 21) { const f32x4 a = (f32x4){ssum[0], ssum[1], ssum[2], ssum[3]} + (f32x4){ssum[4], ssum[5], ssum[6], ssum[7]} + (f32x4){ssum[8], ssum[9], ssum[10], ssum[11]} + (f32x4){ssum[12], ssum[13], ssum[14], ssum[15]};
;                 S.lsum += (a[0] + a[1]) + (a[2] + a[3]); }
.LBB0_416:
.LBB0_417:
	s_barrier
	ds_read_b128 v[80:83], v231
	ds_read_b128 v[242:245], v231 offset:4608
	s_waitcnt lgkmcnt(1)
	v_mfma_f32_32x32x16_bf16 v[112:127], v[80:83], v[174:177], v[96:111]
	ds_read_b128 v[246:249], v231 offset:32
	v_exp_f32_e32 v216, v144
	v_exp_f32_e32 v217, v145
	v_exp_f32_e32 v144, v146
	v_exp_f32_e32 v145, v147
	s_waitcnt lgkmcnt(1)
	v_mfma_f32_32x32x16_bf16 v[80:95], v[242:245], v[174:177], v[96:111]
	ds_read_b128 v[190:193], v231 offset:4640
	v_exp_f32_e32 v146, v148
	v_exp_f32_e32 v147, v149
	s_waitcnt lgkmcnt(1)
	v_mfma_f32_32x32x16_bf16 v[112:127], v[246:249], v[170:173], v[112:127]
	ds_read_b128 v[242:245], v231 offset:64
	v_exp_f32_e32 v148, v150
	v_exp_f32_e32 v149, v151
	s_waitcnt lgkmcnt(1)
	v_mfma_f32_32x32x16_bf16 v[80:95], v[190:193], v[170:173], v[80:95]
	ds_read_b128 v[246:249], v231 offset:4672
	s_waitcnt vmcnt(0)
	ds_write_b128 v232, v[178:181] offset:9216
	ds_write_b128 v232, v[182:185] offset:18432
	ds_write_b128 v232, v[186:189] offset:27648
	v_cvt_pk_bf16_f32 v196, v216, v217
	v_cvt_pk_bf16_f32 v197, v144, v145
	v_cvt_pk_bf16_f32 v198, v146, v147
	v_cvt_pk_bf16_f32 v199, v148, v149
	s_waitcnt lgkmcnt(4)
	v_mfma_f32_32x32x16_bf16 v[112:127], v[242:245], v[166:169], v[112:127]
	ds_read_b128 v[190:193], v231 offset:96
	v_exp_f32_e32 v150, v152
	v_exp_f32_e32 v151, v153
	v_lshl_add_u64 v[152:153], v[206:207], 0, s[100:101]
	ds_read_b128 v[242:245], v231 offset:4704
	global_load_dwordx4 v[178:181], v[152:153], off
	global_load_dwordx4 v[182:185], v[208:209], off offset:384
	global_load_dwordx4 v[186:189], v[214:215], off offset:384
	s_waitcnt lgkmcnt(5)
	v_mfma_f32_32x32x16_bf16 v[80:95], v[246:249], v[166:169], v[80:95]
	v_exp_f32_e32 v214, v154
	v_exp_f32_e32 v215, v155
	s_waitcnt lgkmcnt(1)
	v_mfma_f32_32x32x16_bf16 v[112:127], v[190:193], v[162:165], v[112:127]
	ds_read_b128 v[152:155], v230 offset:36864
	v_exp_f32_e32 v236, v156
	v_exp_f32_e32 v237, v157
	s_waitcnt lgkmcnt(1)
	v_mfma_f32_32x32x16_bf16 v[80:95], v[242:245], v[162:165], v[80:95]
	ds_read_b128 v[190:193], v230 offset:41472
	v_exp_f32_e32 v242, v158
	v_exp_f32_e32 v243, v159
	s_waitcnt lgkmcnt(1)
	v_mfma_f32_32x32x16_bf16 v[48:63], v[152:155], v[196:199], v[48:63]
	ds_read_b128 v[156:159], v230 offset:46080
	v_cvt_pk_bf16_f32 v152, v150, v151
	v_cvt_pk_bf16_f32 v153, v214, v215
	v_cvt_pk_bf16_f32 v154, v236, v237
	v_cvt_pk_bf16_f32 v155, v242, v243
	v_exp_f32_e32 v244, v128
	v_exp_f32_e32 v245, v129
	s_waitcnt lgkmcnt(1)
	v_mfma_f32_32x32x16_bf16 v[32:47], v[190:193], v[196:199], v[32:47]
	ds_read_b128 v[210:213], v230 offset:50688
	v_exp_f32_e32 v246, v130
	v_exp_f32_e32 v247, v131
	s_waitcnt lgkmcnt(1)
	v_mfma_f32_32x32x16_bf16 v[16:31], v[156:159], v[196:199], v[16:31]
	ds_read_b128 v[128:131], v230 offset:36896
	v_exp_f32_e32 v248, v132
	v_exp_f32_e32 v249, v133
	s_waitcnt lgkmcnt(1)
	v_mfma_f32_32x32x16_bf16 v[0:15], v[210:213], v[196:199], v[0:15]
	ds_read_b128 v[156:159], v230 offset:41504
	v_exp_f32_e32 v196, v134
	v_exp_f32_e32 v197, v135
	s_waitcnt lgkmcnt(1)
	v_mfma_f32_32x32x16_bf16 v[48:63], v[128:131], v[152:155], v[48:63]
	ds_read_b128 v[132:135], v230 offset:46112
	v_cvt_pk_bf16_f32 v128, v244, v245
	v_cvt_pk_bf16_f32 v129, v246, v247
	v_cvt_pk_bf16_f32 v130, v248, v249
	v_cvt_pk_bf16_f32 v131, v196, v197
	s_waitcnt lgkmcnt(1)
	v_mfma_f32_32x32x16_bf16 v[32:47], v[156:159], v[152:155], v[32:47]
	ds_read_b128 v[190:193], v230 offset:50720
	v_exp_f32_e32 v198, v136
	v_exp_f32_e32 v199, v137
	s_waitcnt lgkmcnt(1)
	v_mfma_f32_32x32x16_bf16 v[16:31], v[132:135], v[152:155], v[16:31]
	ds_read_b128 v[156:159], v230 offset:36928
	v_exp_f32_e32 v210, v138
	v_exp_f32_e32 v211, v139
	s_waitcnt lgkmcnt(1)
	v_mfma_f32_32x32x16_bf16 v[0:15], v[190:193], v[152:155], v[0:15]
	ds_read_b128 v[132:135], v230 offset:41536
	v_exp_f32_e32 v190, v140
	v_exp_f32_e32 v191, v141
	s_waitcnt lgkmcnt(1)
	v_mfma_f32_32x32x16_bf16 v[48:63], v[156:159], v[128:131], v[48:63]
	ds_read_b128 v[136:139], v230 offset:46144
	v_exp_f32_e32 v156, v142
	v_exp_f32_e32 v157, v143
	v_cvt_pk_bf16_f32 v140, v198, v199
	v_cvt_pk_bf16_f32 v141, v210, v211
	v_cvt_pk_bf16_f32 v142, v190, v191
	v_cvt_pk_bf16_f32 v143, v156, v157
	s_waitcnt lgkmcnt(1)
	v_mfma_f32_32x32x16_bf16 v[32:47], v[132:135], v[128:131], v[32:47]
	ds_read_b128 v[152:155], v230 offset:50752
	v_add_f32_e64 v158, v190, v236
	v_add_f32_e64 v159, v191, v237
	v_add_f32_e64 v156, v156, v242
	v_add_f32_e64 v157, v157, v243
	v_pk_add_f32 v[190:191], v[210:211], v[214:215]
	v_pk_add_f32 v[150:151], v[198:199], v[150:151]
	v_pk_add_f32 v[146:147], v[248:249], v[146:147]
	v_pk_add_f32 v[192:193], v[244:245], v[216:217]
	v_pk_add_f32 v[148:149], v[196:197], v[148:149]
	v_pk_add_f32 v[144:145], v[246:247], v[144:145]
	s_waitcnt lgkmcnt(1)
	v_mfma_f32_32x32x16_bf16 v[16:31], v[136:139], v[128:131], v[16:31]
	v_add_f32_e64 v136, v144, v148
	v_add_f32_e64 v137, v145, v149
	v_add_f32_e64 v138, v192, v146
	v_add_f32_e64 v139, v193, v147
	v_add_f32_e64 v136, v190, v136
	v_add_f32_e64 v137, v191, v137
	v_pk_add_f32 v[138:139], v[150:151], v[138:139]
	v_pk_add_f32 v[136:137], v[156:157], v[136:137]
	v_pk_add_f32 v[138:139], v[158:159], v[138:139]
	ds_read_b128 v[132:135], v230 offset:36960
	v_pk_mov_b32 v[144:145], v[138:139], v[136:137] op_sel:[1,0]
	v_mov_b32_e32 v139, v137
	v_pk_add_f32 v[136:137], v[144:145], v[138:139]
	s_nop 0
	v_add_f32_e32 v136, v136, v137
	v_add_f32_e32 v216, v234, v136
	s_waitcnt lgkmcnt(1)
	v_mfma_f32_32x32x16_bf16 v[0:15], v[152:155], v[128:131], v[0:15]
	ds_read_b128 v[136:139], v230 offset:41568
	v_max3_f32 v128, v112, v113, v80
	v_max3_f32 v144, v114, v115, v81
	v_max3_f32 v145, v128, v82, v83
	s_waitcnt lgkmcnt(1)
	v_mfma_f32_32x32x16_bf16 v[48:63], v[132:135], v[140:143], v[48:63]
	ds_read_b128 v[128:131], v230 offset:46176
	v_max3_f32 v132, v145, v116, v117
	v_max3_f32 v133, v144, v118, v119
	v_max3_f32 v144, v132, v84, v85
	v_max3_f32 v145, v133, v86, v87
	s_waitcnt lgkmcnt(1)
	v_mfma_f32_32x32x16_bf16 v[32:47], v[136:139], v[140:143], v[32:47]
	ds_read_b128 v[132:135], v230 offset:50784
	v_max3_f32 v136, v144, v120, v121
	v_max3_f32 v137, v145, v122, v123
	v_max3_f32 v136, v136, v88, v89
	v_max3_f32 v137, v137, v90, v91
	s_waitcnt lgkmcnt(1)
	v_mfma_f32_32x32x16_bf16 v[16:31], v[128:131], v[140:143], v[16:31]
	v_max3_f32 v128, v136, v124, v125
	v_max3_f32 v129, v137, v126, v127
	v_max3_f32 v128, v128, v92, v93
	v_max3_f32 v129, v129, v94, v95
	v_max_f32_e32 v128, v128, v129
	v_mov_b32_e32 v129, v128
	s_waitcnt lgkmcnt(0)
	v_mfma_f32_32x32x16_bf16 v[0:15], v[132:135], v[140:143], v[0:15]
	v_permlane32_swap_b32_e32 v128, v129
	v_max_f32_e32 v128, v128, v129
	v_cmp_lt_f32_e32 vcc, s3, v128
	s_cbranch_vccz .LBB0_413
; __device__ __forceinline__ float fast_exp2(float x) { return __builtin_amdgcn_exp2f(x); }
; template <int DV, int PAR, bool KW = true, bool KL = true, bool VL = true>
; __device__ __forceinline__ void attn_iter_full(AttnState<DV>& S, int t, LAS unsigned char* lds) {
;     ...
;     if (__any(mx > 8.0f)) {
;         const float dl = fmaxf(mx, 0.f), alpha = fast_exp2(-dl);
;         S.mrun += dl; S.lsum *= alpha;
; #pragma unroll
;         for (int i = 0; i < 16; ++i) { sn0[i] -= dl; sn1[i] -= dl; S.negm[i] = -S.mrun; }
; #pragma unroll
;         for (int d = 0; d < NDB; ++d)
; #pragma unroll
;             for (int i = 0; i < 16; ++i) S.o[d][i] *= alpha;
;     }
	v_max_f32_e32 v64, v128, v128
	v_max_f32_e32 v65, 0, v64
	v_exp_f32_e64 v66, -v65
	v_add_f32_e32 v233, v233, v65
	v_xor_b32_e32 v64, 0x80000000, v233
	v_sub_f32_e32 v127, v127, v65
	v_mul_f32_e32 v216, v216, v66
	v_sub_f32_e32 v126, v126, v65
	v_sub_f32_e32 v125, v125, v65
	v_sub_f32_e32 v124, v124, v65
	v_sub_f32_e32 v123, v123, v65
	v_sub_f32_e32 v122, v122, v65
	v_sub_f32_e32 v121, v121, v65
	v_sub_f32_e32 v120, v120, v65
	v_sub_f32_e32 v119, v119, v65
	v_sub_f32_e32 v118, v118, v65
	v_sub_f32_e32 v117, v117, v65
	v_sub_f32_e32 v116, v116, v65
	v_sub_f32_e32 v115, v115, v65
	v_sub_f32_e32 v114, v114, v65
	v_sub_f32_e32 v113, v113, v65
	v_sub_f32_e32 v112, v112, v65
	v_sub_f32_e32 v95, v95, v65
	v_sub_f32_e32 v94, v94, v65
	v_sub_f32_e32 v93, v93, v65
	v_sub_f32_e32 v92, v92, v65
	v_sub_f32_e32 v91, v91, v65
	v_sub_f32_e32 v90, v90, v65
	v_sub_f32_e32 v89, v89, v65
	v_sub_f32_e32 v88, v88, v65
	v_sub_f32_e32 v87, v87, v65
	v_sub_f32_e32 v86, v86, v65
	v_sub_f32_e32 v85, v85, v65
	v_sub_f32_e32 v84, v84, v65
	v_sub_f32_e32 v83, v83, v65
	v_sub_f32_e32 v82, v82, v65
	v_sub_f32_e32 v81, v81, v65
	v_sub_f32_e32 v80, v80, v65
	v_pk_mul_f32 v[62:63], v[62:63], v[66:67] op_sel_hi:[1,0]
	v_pk_mul_f32 v[60:61], v[60:61], v[66:67] op_sel_hi:[1,0]
	v_pk_mul_f32 v[58:59], v[58:59], v[66:67] op_sel_hi:[1,0]
	v_pk_mul_f32 v[56:57], v[56:57], v[66:67] op_sel_hi:[1,0]
	v_pk_mul_f32 v[54:55], v[54:55], v[66:67] op_sel_hi:[1,0]
	v_pk_mul_f32 v[52:53], v[52:53], v[66:67] op_sel_hi:[1,0]
	v_pk_mul_f32 v[50:51], v[50:51], v[66:67] op_sel_hi:[1,0]
	v_pk_mul_f32 v[48:49], v[48:49], v[66:67] op_sel_hi:[1,0]
	v_pk_mul_f32 v[46:47], v[46:47], v[66:67] op_sel_hi:[1,0]
	v_pk_mul_f32 v[44:45], v[44:45], v[66:67] op_sel_hi:[1,0]
	v_pk_mul_f32 v[42:43], v[42:43], v[66:67] op_sel_hi:[1,0]
	v_pk_mul_f32 v[40:41], v[40:41], v[66:67] op_sel_hi:[1,0]
	v_pk_mul_f32 v[38:39], v[38:39], v[66:67] op_sel_hi:[1,0]
	v_pk_mul_f32 v[36:37], v[36:37], v[66:67] op_sel_hi:[1,0]
	v_pk_mul_f32 v[34:35], v[34:35], v[66:67] op_sel_hi:[1,0]
	v_pk_mul_f32 v[32:33], v[32:33], v[66:67] op_sel_hi:[1,0]
	v_pk_mul_f32 v[30:31], v[30:31], v[66:67] op_sel_hi:[1,0]
	v_pk_mul_f32 v[28:29], v[28:29], v[66:67] op_sel_hi:[1,0]
	v_pk_mul_f32 v[26:27], v[26:27], v[66:67] op_sel_hi:[1,0]
	v_pk_mul_f32 v[24:25], v[24:25], v[66:67] op_sel_hi:[1,0]
	v_pk_mul_f32 v[22:23], v[22:23], v[66:67] op_sel_hi:[1,0]
	v_pk_mul_f32 v[20:21], v[20:21], v[66:67] op_sel_hi:[1,0]
	v_pk_mul_f32 v[18:19], v[18:19], v[66:67] op_sel_hi:[1,0]
	v_pk_mul_f32 v[16:17], v[16:17], v[66:67] op_sel_hi:[1,0]
	v_pk_mul_f32 v[14:15], v[14:15], v[66:67] op_sel_hi:[1,0]
	v_pk_mul_f32 v[12:13], v[12:13], v[66:67] op_sel_hi:[1,0]
	v_pk_mul_f32 v[10:11], v[10:11], v[66:67] op_sel_hi:[1,0]
	v_pk_mul_f32 v[8:9], v[8:9], v[66:67] op_sel_hi:[1,0]
	v_pk_mul_f32 v[6:7], v[6:7], v[66:67] op_sel_hi:[1,0]
	v_pk_mul_f32 v[4:5], v[4:5], v[66:67] op_sel_hi:[1,0]
	v_pk_mul_f32 v[2:3], v[2:3], v[66:67] op_sel_hi:[1,0]
	v_pk_mul_f32 v[0:1], v[0:1], v[66:67] op_sel_hi:[1,0]
	v_mov_b32_e32 v65, v64
	v_mov_b32_e32 v66, v64
	v_mov_b32_e32 v67, v64
	v_mov_b32_e32 v68, v64
	v_mov_b32_e32 v69, v64
	v_mov_b32_e32 v70, v64
	v_mov_b32_e32 v71, v64
	v_mov_b32_e32 v72, v64
	v_mov_b32_e32 v73, v64
	v_mov_b32_e32 v74, v64
	v_mov_b32_e32 v75, v64
	v_mov_b32_e32 v76, v64
	v_mov_b32_e32 v77, v64
	v_mov_b32_e32 v78, v64
	v_mov_b32_e32 v79, v64
	v_mov_b32_e32 v96, v64
	v_mov_b32_e32 v97, v64
	v_mov_b32_e32 v98, v64
	v_mov_b32_e32 v99, v64
	v_mov_b32_e32 v100, v64
	v_mov_b32_e32 v101, v64
	v_mov_b32_e32 v102, v64
	v_mov_b32_e32 v103, v64
	v_mov_b32_e32 v104, v64
	v_mov_b32_e32 v105, v64
	v_mov_b32_e32 v106, v64
	v_mov_b32_e32 v107, v64
	v_mov_b32_e32 v108, v64
	v_mov_b32_e32 v109, v64
	v_mov_b32_e32 v110, v64
	v_mov_b32_e32 v111, v64
	s_branch .LBB0_413

; #define LAS __attribute__((address_space(3)))
; template <int DV, int PAR, bool KW = true, bool KL = true, bool VL = true>
; __device__ __forceinline__ void attn_iter_full(AttnState<DV>& S, int t, LAS unsigned char* lds) {
;     ...
; #pragma unroll
;     for (int i = 0; i < NS; ++i) {
;         if (i + PD < NS) fr[(i + PD) % (PD + 1)] = AT_FRAG(i + PD);
;         if (i == 3) {
;             if (KW) *(LAS u32x4*)(lds + AT_K0 + PAR * AT_KB + S.kl) = S.kreg;
;             LAS unsigned char* W = lds + AT_V0 + (PAR ^ 1) * AT_VB + S.vl; *(LAS u32x4*)W = S.vreg0; if (DV == 128) *(LAS u32x4*)(W + 64 * 144) = S.vreg1; }
;         if (i == 5) { if (KL) S.kreg = *(const u32x4*)(S.kg + (size_t)(t + 3) * 4096);
;             if (VL) { S.vreg0 = *(const u32x4*)(S.vg + (t + 2) * 64); if (DV == 128) S.vreg1 = *(const u32x4*)(S.vg + (size_t)64 * TK + (t + 2) * 64); } }
;         if (i < 8) { if (i & 1) sn1 = MFMA32(fr[i % (PD + 1)], S.qr[i >> 1], sn1); else sn0 = MFMA32(fr[i % (PD + 1)], S.qr[i >> 1], sn0); }
;         else { const int j = i - 8; S.o[j % NDB] = MFMA32(fr[i % (PD + 1)], __builtin_bit_cast(bf16x8, pw[j / NDB]), S.o[j % NDB]); }
; #pragma unroll
;         for (int u = 0; u < NU; ++u) {
;             if (u * NS / NU != i) continue;
;             if (u < 20) {
;                 const int q = u / 5, r = u % 5;
;                 if (r < 4) { const int e = 8 * q + 2 * r;
;                     if (e < 16) { C0[e] = fast_exp2(C0[e]); C0[e + 1] = fast_exp2(C0[e + 1]); }
;                     else { C1[e - 16] = fast_exp2(C1[e - 16]); C1[e - 15] = fast_exp2(C1[e - 15]); } }
;                 else { if (q < 2) { const int b0 = 8 * q; pw[q].x = pk2(C0[b0], C0[b0 + 1]); pw[q].y = pk2(C0[b0 + 2], C0[b0 + 3]); pw[q].z = pk2(C0[b0 + 4], C0[b0 + 5]); pw[q].w = pk2(C0[b0 + 6], C0[b0 + 7]); }
;                        else { const int b0 = 8 * (q - 2); pw[q].x = pk2(C1[b0], C1[b0 + 1]); pw[q].y = pk2(C1[b0 + 2], C1[b0 + 3]); pw[q].z = pk2(C1[b0 + 4], C1[b0 + 5]); pw[q].w = pk2(C1[b0 + 6], C1[b0 + 7]); } }
;             } else if (u == 20) { ssum = C0 + C1; }
;             else if (u == 21) { const f32x4 a = (f32x4){ssum[0], ssum[1], ssum[2], ssum[3]} + (f32x4){ssum[4], ssum[5], ssum[6], ssum[7]} + (f32x4){ssum[8], ssum[9], ssum[10], ssum[11]} + (f32x4){ssum[12], ssum[13], ssum[14], ssum[15]};
;                 S.lsum += (a[0] + a[1]) + (a[2] + a[3]); }
.LBB0_427:
	ds_read_b128 v[64:67], v234 offset:9216
	ds_read_b128 v[68:71], v234 offset:13824
	s_waitcnt lgkmcnt(1)
	v_mfma_f32_32x32x16_bf16 v[144:159], v[64:67], v[174:177], v[96:111]
	ds_read_b128 v[72:75], v234 offset:9248
	v_exp_f32_e32 v64, v114
	v_exp_f32_e32 v66, v112
	v_exp_f32_e32 v67, v113
	v_exp_f32_e32 v65, v115
	s_waitcnt lgkmcnt(1)
	v_mfma_f32_32x32x16_bf16 v[128:143], v[68:71], v[174:177], v[96:111]
	ds_read_b128 v[76:79], v234 offset:13856
	v_exp_f32_e32 v68, v116
	v_exp_f32_e32 v69, v117
	s_waitcnt lgkmcnt(1)
	v_mfma_f32_32x32x16_bf16 v[144:159], v[72:75], v[170:173], v[144:159]
	ds_read_b128 v[112:115], v234 offset:9280
	v_exp_f32_e32 v70, v118
	v_exp_f32_e32 v71, v119
	s_waitcnt lgkmcnt(1)
	v_mfma_f32_32x32x16_bf16 v[128:143], v[76:79], v[170:173], v[128:143]
	ds_read_b128 v[116:119], v234 offset:13888
	s_waitcnt vmcnt(0)
	ds_write_b128 v235, v[186:189]
	ds_write_b128 v235, v[178:181] offset:36864
	ds_write_b128 v235, v[182:185] offset:46080
	v_cvt_pk_bf16_f32 v74, v66, v67
	v_cvt_pk_bf16_f32 v75, v64, v65
	v_cvt_pk_bf16_f32 v76, v68, v69
	v_cvt_pk_bf16_f32 v77, v70, v71
	s_waitcnt lgkmcnt(4)
	v_mfma_f32_32x32x16_bf16 v[144:159], v[112:115], v[166:169], v[144:159]
	ds_read_b128 v[190:193], v234 offset:9312
	v_exp_f32_e32 v72, v120
	v_exp_f32_e32 v73, v121
	ds_read_b128 v[112:115], v234 offset:13920
	global_load_dwordx4 v[178:181], v[206:207], off
	global_load_dwordx4 v[182:185], v[208:209], off offset:256
	v_lshl_add_u64 v[214:215], v[208:209], 0, s[4:5]
	global_load_dwordx4 v[186:189], v[214:215], off offset:256
	s_waitcnt lgkmcnt(5)
	v_mfma_f32_32x32x16_bf16 v[128:143], v[116:119], v[166:169], v[128:143]
	v_exp_f32_e32 v196, v122
	v_exp_f32_e32 v197, v123
	s_waitcnt lgkmcnt(1)
	v_mfma_f32_32x32x16_bf16 v[144:159], v[190:193], v[162:165], v[144:159]
	ds_read_b128 v[116:119], v233 offset:18432
	v_exp_f32_e32 v124, v124
	v_exp_f32_e32 v125, v125
	s_waitcnt lgkmcnt(1)
	v_mfma_f32_32x32x16_bf16 v[128:143], v[112:115], v[162:165], v[128:143]
	ds_read_b128 v[120:123], v233 offset:23040
	v_exp_f32_e32 v126, v126
	v_exp_f32_e32 v127, v127
	s_waitcnt lgkmcnt(1)
	v_mfma_f32_32x32x16_bf16 v[0:15], v[116:119], v[74:77], v[0:15]
	ds_read_b128 v[112:115], v233 offset:27648
	v_cvt_pk_bf16_f32 v116, v72, v73
	v_cvt_pk_bf16_f32 v117, v196, v197
	v_cvt_pk_bf16_f32 v118, v124, v125
	v_cvt_pk_bf16_f32 v119, v126, v127
	v_exp_f32_e32 v190, v80
	v_exp_f32_e32 v191, v81
	s_waitcnt lgkmcnt(1)
	v_mfma_f32_32x32x16_bf16 v[48:63], v[120:123], v[74:77], v[48:63]
	ds_read_b128 v[78:81], v233 offset:32256
	v_exp_f32_e32 v192, v82
	v_exp_f32_e32 v193, v83
	s_waitcnt lgkmcnt(1)
	v_mfma_f32_32x32x16_bf16 v[32:47], v[112:115], v[74:77], v[32:47]
	ds_read_b128 v[120:123], v233 offset:18464
	v_exp_f32_e32 v198, v84
	v_exp_f32_e32 v199, v85
	s_waitcnt lgkmcnt(1)
	v_mfma_f32_32x32x16_bf16 v[16:31], v[78:81], v[74:77], v[16:31]
	ds_read_b128 v[82:85], v233 offset:23072
	v_exp_f32_e32 v242, v86
	v_exp_f32_e32 v243, v87
	s_waitcnt lgkmcnt(1)
	v_mfma_f32_32x32x16_bf16 v[0:15], v[120:123], v[116:119], v[0:15]
	ds_read_b128 v[74:77], v233 offset:27680
	v_cvt_pk_bf16_f32 v78, v190, v191
	v_cvt_pk_bf16_f32 v79, v192, v193
	v_cvt_pk_bf16_f32 v80, v198, v199
	v_cvt_pk_bf16_f32 v81, v242, v243
	s_waitcnt lgkmcnt(1)
	v_mfma_f32_32x32x16_bf16 v[48:63], v[82:85], v[116:119], v[48:63]
	ds_read_b128 v[112:115], v233 offset:32288
	v_exp_f32_e32 v120, v88
	v_exp_f32_e32 v121, v89
	s_waitcnt lgkmcnt(1)
	v_mfma_f32_32x32x16_bf16 v[32:47], v[74:77], v[116:119], v[32:47]
	ds_read_b128 v[82:85], v233 offset:18496
	v_exp_f32_e32 v122, v90
	v_exp_f32_e32 v123, v91
	s_waitcnt lgkmcnt(1)
	v_mfma_f32_32x32x16_bf16 v[16:31], v[112:115], v[116:119], v[16:31]
	ds_read_b128 v[74:77], v233 offset:23104
	v_exp_f32_e32 v112, v92
	v_exp_f32_e32 v113, v93
	s_waitcnt lgkmcnt(1)
	v_mfma_f32_32x32x16_bf16 v[0:15], v[82:85], v[78:81], v[0:15]
	ds_read_b128 v[86:89], v233 offset:27712
	v_exp_f32_e32 v94, v94
	v_exp_f32_e32 v95, v95
	v_cvt_pk_bf16_f32 v82, v120, v121
	v_cvt_pk_bf16_f32 v83, v122, v123
	v_cvt_pk_bf16_f32 v84, v112, v113
	v_cvt_pk_bf16_f32 v85, v94, v95
	s_waitcnt lgkmcnt(1)
	v_mfma_f32_32x32x16_bf16 v[48:63], v[74:77], v[78:81], v[48:63]
	ds_read_b128 v[90:93], v233 offset:32320
	v_add_f32_e64 v74, v124, v112
	v_add_f32_e64 v75, v125, v113
	v_add_f32_e64 v76, v126, v94
	v_add_f32_e64 v77, v127, v95
	v_pk_add_f32 v[94:95], v[196:197], v[122:123]
	v_pk_add_f32 v[72:73], v[72:73], v[120:121]
	v_pk_add_f32 v[68:69], v[68:69], v[198:199]
	v_pk_add_f32 v[112:113], v[66:67], v[190:191]
	v_pk_add_f32 v[70:71], v[70:71], v[242:243]
	v_pk_add_f32 v[114:115], v[64:65], v[192:193]
	s_waitcnt lgkmcnt(1)
	v_mfma_f32_32x32x16_bf16 v[32:47], v[86:89], v[78:81], v[32:47]
	v_add_f32_e64 v70, v114, v70
	v_add_f32_e64 v71, v115, v71
	v_add_f32_e64 v68, v112, v68
	v_add_f32_e64 v69, v113, v69
	v_add_f32_e64 v70, v94, v70
	v_add_f32_e64 v71, v95, v71
	v_pk_add_f32 v[68:69], v[72:73], v[68:69]
	ds_read_b128 v[64:67], v233 offset:18528
	v_pk_add_f32 v[70:71], v[76:77], v[70:71]
	v_pk_add_f32 v[68:69], v[74:75], v[68:69]
	s_nop 0
	v_pk_mov_b32 v[72:73], v[68:69], v[70:71] op_sel:[1,0]
	v_mov_b32_e32 v69, v71
	v_pk_add_f32 v[68:69], v[72:73], v[68:69]
	s_nop 0
	v_add_f32_e32 v68, v68, v69
	v_add_f32_e32 v237, v216, v68
	s_waitcnt lgkmcnt(1)
	v_mfma_f32_32x32x16_bf16 v[16:31], v[90:93], v[78:81], v[16:31]
	ds_read_b128 v[68:71], v233 offset:23136
	v_max3_f32 v72, v144, v145, v128
	v_max3_f32 v76, v146, v147, v129
	v_max3_f32 v77, v72, v130, v131
	s_waitcnt lgkmcnt(1)
	v_mfma_f32_32x32x16_bf16 v[0:15], v[64:67], v[82:85], v[0:15]
	ds_read_b128 v[72:75], v233 offset:27744
	v_max3_f32 v64, v77, v148, v149
	v_max3_f32 v65, v76, v150, v151
	v_max3_f32 v76, v64, v132, v133
	v_max3_f32 v77, v65, v134, v135
	s_waitcnt lgkmcnt(1)
	v_mfma_f32_32x32x16_bf16 v[48:63], v[68:71], v[82:85], v[48:63]
	ds_read_b128 v[64:67], v233 offset:32352
	v_max3_f32 v68, v76, v152, v153
	v_max3_f32 v69, v77, v154, v155
	v_max3_f32 v68, v68, v136, v137
	v_max3_f32 v69, v69, v138, v139
	s_waitcnt lgkmcnt(1)
	v_mfma_f32_32x32x16_bf16 v[32:47], v[72:75], v[82:85], v[32:47]
	v_max3_f32 v68, v68, v156, v157
	v_max3_f32 v69, v69, v158, v159
	v_max3_f32 v68, v68, v140, v141
	v_max3_f32 v69, v69, v142, v143
	v_max_f32_e32 v68, v68, v69
	v_mov_b32_e32 v69, v68
	s_waitcnt lgkmcnt(0)
	v_mfma_f32_32x32x16_bf16 v[16:31], v[64:67], v[82:85], v[16:31]
	v_permlane32_swap_b32_e32 v68, v69
	v_max_f32_e32 v64, v68, v69
	v_cmp_lt_f32_e32 vcc, s3, v64
	s_cbranch_vccz .LBB0_429
; __device__ __forceinline__ float fast_exp2(float x) { return __builtin_amdgcn_exp2f(x); }
; template <int DV, int PAR, bool KW = true, bool KL = true, bool VL = true>
; __device__ __forceinline__ void attn_iter_full(AttnState<DV>& S, int t, LAS unsigned char* lds) {
;     ...
;     if (__any(mx > 8.0f)) {
;         const float dl = fmaxf(mx, 0.f), alpha = fast_exp2(-dl);
;         S.mrun += dl; S.lsum *= alpha;
; #pragma unroll
;         for (int i = 0; i < 16; ++i) { sn0[i] -= dl; sn1[i] -= dl; S.negm[i] = -S.mrun; }
; #pragma unroll
;         for (int d = 0; d < NDB; ++d)
; #pragma unroll
;             for (int i = 0; i < 16; ++i) S.o[d][i] *= alpha;
;     }
	v_max_f32_e32 v64, v64, v64
	v_max_f32_e32 v66, 0, v64
	v_exp_f32_e64 v68, -v66
	v_add_f32_e32 v236, v236, v66
	v_xor_b32_e32 v64, 0x80000000, v236
	v_pk_add_f32 v[144:145], v[144:145], v[66:67] op_sel_hi:[1,0] neg_lo:[0,1] neg_hi:[0,1]
	v_mul_f32_e32 v237, v237, v68
	v_pk_add_f32 v[128:129], v[128:129], v[66:67] op_sel_hi:[1,0] neg_lo:[0,1] neg_hi:[0,1]
	v_pk_add_f32 v[146:147], v[146:147], v[66:67] op_sel_hi:[1,0] neg_lo:[0,1] neg_hi:[0,1]
	v_pk_add_f32 v[130:131], v[130:131], v[66:67] op_sel_hi:[1,0] neg_lo:[0,1] neg_hi:[0,1]
	v_pk_add_f32 v[148:149], v[148:149], v[66:67] op_sel_hi:[1,0] neg_lo:[0,1] neg_hi:[0,1]
	v_pk_add_f32 v[132:133], v[132:133], v[66:67] op_sel_hi:[1,0] neg_lo:[0,1] neg_hi:[0,1]
	v_pk_add_f32 v[150:151], v[150:151], v[66:67] op_sel_hi:[1,0] neg_lo:[0,1] neg_hi:[0,1]
	v_pk_add_f32 v[134:135], v[134:135], v[66:67] op_sel_hi:[1,0] neg_lo:[0,1] neg_hi:[0,1]
	v_pk_add_f32 v[152:153], v[152:153], v[66:67] op_sel_hi:[1,0] neg_lo:[0,1] neg_hi:[0,1]
	v_pk_add_f32 v[136:137], v[136:137], v[66:67] op_sel_hi:[1,0] neg_lo:[0,1] neg_hi:[0,1]
	v_pk_add_f32 v[154:155], v[154:155], v[66:67] op_sel_hi:[1,0] neg_lo:[0,1] neg_hi:[0,1]
	v_pk_add_f32 v[138:139], v[138:139], v[66:67] op_sel_hi:[1,0] neg_lo:[0,1] neg_hi:[0,1]
	v_pk_add_f32 v[156:157], v[156:157], v[66:67] op_sel_hi:[1,0] neg_lo:[0,1] neg_hi:[0,1]
	v_pk_add_f32 v[140:141], v[140:141], v[66:67] op_sel_hi:[1,0] neg_lo:[0,1] neg_hi:[0,1]
	v_pk_add_f32 v[158:159], v[158:159], v[66:67] op_sel_hi:[1,0] neg_lo:[0,1] neg_hi:[0,1]
	v_pk_add_f32 v[142:143], v[142:143], v[66:67] op_sel_hi:[1,0] neg_lo:[0,1] neg_hi:[0,1]
	v_pk_mul_f32 v[14:15], v[14:15], v[68:69] op_sel_hi:[1,0]
	v_pk_mul_f32 v[12:13], v[12:13], v[68:69] op_sel_hi:[1,0]
	v_pk_mul_f32 v[10:11], v[10:11], v[68:69] op_sel_hi:[1,0]
	v_pk_mul_f32 v[8:9], v[8:9], v[68:69] op_sel_hi:[1,0]
	v_pk_mul_f32 v[6:7], v[6:7], v[68:69] op_sel_hi:[1,0]
	v_pk_mul_f32 v[4:5], v[4:5], v[68:69] op_sel_hi:[1,0]
	v_pk_mul_f32 v[2:3], v[2:3], v[68:69] op_sel_hi:[1,0]
	v_pk_mul_f32 v[0:1], v[0:1], v[68:69] op_sel_hi:[1,0]
	v_pk_mul_f32 v[62:63], v[62:63], v[68:69] op_sel_hi:[1,0]
	v_pk_mul_f32 v[60:61], v[60:61], v[68:69] op_sel_hi:[1,0]
	v_pk_mul_f32 v[58:59], v[58:59], v[68:69] op_sel_hi:[1,0]
	v_pk_mul_f32 v[56:57], v[56:57], v[68:69] op_sel_hi:[1,0]
	v_pk_mul_f32 v[54:55], v[54:55], v[68:69] op_sel_hi:[1,0]
	v_pk_mul_f32 v[52:53], v[52:53], v[68:69] op_sel_hi:[1,0]
	v_pk_mul_f32 v[50:51], v[50:51], v[68:69] op_sel_hi:[1,0]
	v_pk_mul_f32 v[48:49], v[48:49], v[68:69] op_sel_hi:[1,0]
	v_pk_mul_f32 v[46:47], v[46:47], v[68:69] op_sel_hi:[1,0]
	v_pk_mul_f32 v[44:45], v[44:45], v[68:69] op_sel_hi:[1,0]
	v_pk_mul_f32 v[42:43], v[42:43], v[68:69] op_sel_hi:[1,0]
	v_pk_mul_f32 v[40:41], v[40:41], v[68:69] op_sel_hi:[1,0]
	v_pk_mul_f32 v[38:39], v[38:39], v[68:69] op_sel_hi:[1,0]
	v_pk_mul_f32 v[36:37], v[36:37], v[68:69] op_sel_hi:[1,0]
	v_pk_mul_f32 v[34:35], v[34:35], v[68:69] op_sel_hi:[1,0]
	v_pk_mul_f32 v[32:33], v[32:33], v[68:69] op_sel_hi:[1,0]
	v_pk_mul_f32 v[30:31], v[30:31], v[68:69] op_sel_hi:[1,0]
	v_pk_mul_f32 v[28:29], v[28:29], v[68:69] op_sel_hi:[1,0]
	v_pk_mul_f32 v[26:27], v[26:27], v[68:69] op_sel_hi:[1,0]
	v_pk_mul_f32 v[24:25], v[24:25], v[68:69] op_sel_hi:[1,0]
	v_pk_mul_f32 v[22:23], v[22:23], v[68:69] op_sel_hi:[1,0]
	v_pk_mul_f32 v[20:21], v[20:21], v[68:69] op_sel_hi:[1,0]
	v_pk_mul_f32 v[18:19], v[18:19], v[68:69] op_sel_hi:[1,0]
	v_pk_mul_f32 v[16:17], v[16:17], v[68:69] op_sel_hi:[1,0]
	v_mov_b32_e32 v65, v64
	v_mov_b32_e32 v66, v64
	v_mov_b32_e32 v67, v64
	v_mov_b32_e32 v68, v64
	v_mov_b32_e32 v69, v64
	v_mov_b32_e32 v70, v64
	v_mov_b32_e32 v71, v64
	v_mov_b32_e32 v72, v64
	v_mov_b32_e32 v73, v64
	v_mov_b32_e32 v74, v64
	v_mov_b32_e32 v75, v64
	v_mov_b32_e32 v76, v64
	v_mov_b32_e32 v77, v64
	v_mov_b32_e32 v78, v64
	v_mov_b32_e32 v79, v64
	v_mov_b32_e32 v96, v64
	v_mov_b32_e32 v97, v64
	v_mov_b32_e32 v98, v64
	v_mov_b32_e32 v99, v64
	v_mov_b32_e32 v100, v64
	v_mov_b32_e32 v101, v64
	v_mov_b32_e32 v102, v64
	v_mov_b32_e32 v103, v64
	v_mov_b32_e32 v104, v64
	v_mov_b32_e32 v105, v64
	v_mov_b32_e32 v106, v64
	v_mov_b32_e32 v107, v64
	v_mov_b32_e32 v108, v64
	v_mov_b32_e32 v109, v64
	v_mov_b32_e32 v110, v64
	v_mov_b32_e32 v111, v64
	s_branch .LBB0_430
; #define LAS __attribute__((address_space(3)))
; template <int DV, int PAR, bool KW = true, bool KL = true, bool VL = true>
; __device__ __forceinline__ void attn_iter_full(AttnState<DV>& S, int t, LAS unsigned char* lds) {
;     ...
;     for (int i = 0; i < NS; ++i) {
;         if (i + PD < NS) fr[(i + PD) % (PD + 1)] = AT_FRAG(i + PD);
;         if (i == 3) {
;             if (KW) *(LAS u32x4*)(lds + AT_K0 + PAR * AT_KB + S.kl) = S.kreg;
;             LAS unsigned char* W = lds + AT_V0 + (PAR ^ 1) * AT_VB + S.vl; *(LAS u32x4*)W = S.vreg0; if (DV == 128) *(LAS u32x4*)(W + 64 * 144) = S.vreg1; }
;         if (i == 5) { if (KL) S.kreg = *(const u32x4*)(S.kg + (size_t)(t + 3) * 4096);
;             if (VL) { S.vreg0 = *(const u32x4*)(S.vg + (t + 2) * 64); if (DV == 128) S.vreg1 = *(const u32x4*)(S.vg + (size_t)64 * TK + (t + 2) * 64); } }
;         if (i < 8) { if (i & 1) sn1 = MFMA32(fr[i % (PD + 1)], S.qr[i >> 1], sn1); else sn0 = MFMA32(fr[i % (PD + 1)], S.qr[i >> 1], sn0); }
;         else { const int j = i - 8; S.o[j % NDB] = MFMA32(fr[i % (PD + 1)], __builtin_bit_cast(bf16x8, pw[j / NDB]), S.o[j % NDB]); }
; #pragma unroll
;         for (int u = 0; u < NU; ++u) {
;             if (u * NS / NU != i) continue;
;             if (u < 20) {
;                 const int q = u / 5, r = u % 5;
;                 if (r < 4) { const int e = 8 * q + 2 * r;
;                     if (e < 16) { C0[e] = fast_exp2(C0[e]); C0[e + 1] = fast_exp2(C0[e + 1]); }
;                     else { C1[e - 16] = fast_exp2(C1[e - 16]); C1[e - 15] = fast_exp2(C1[e - 15]); } }
;                 else { if (q < 2) { const int b0 = 8 * q; pw[q].x = pk2(C0[b0], C0[b0 + 1]); pw[q].y = pk2(C0[b0 + 2], C0[b0 + 3]); pw[q].z = pk2(C0[b0 + 4], C0[b0 + 5]); pw[q].w = pk2(C0[b0 + 6], C0[b0 + 7]); }
;                        else { const int b0 = 8 * (q - 2); pw[q].x = pk2(C1[b0], C1[b0 + 1]); pw[q].y = pk2(C1[b0 + 2], C1[b0 + 3]); pw[q].z = pk2(C1[b0 + 4], C1[b0 + 5]); pw[q].w = pk2(C1[b0 + 6], C1[b0 + 7]); } }
;             } else if (u == 20) { ssum = C0 + C1; }
;             else if (u == 21) { const f32x4 a = (f32x4){ssum[0], ssum[1], ssum[2], ssum[3]} + (f32x4){ssum[4], ssum[5], ssum[6], ssum[7]} + (f32x4){ssum[8], ssum[9], ssum[10], ssum[11]} + (f32x4){ssum[12], ssum[13], ssum[14], ssum[15]};
;                 S.lsum += (a[0] + a[1]) + (a[2] + a[3]); }
.LBB0_429:
.LBB0_430:
	s_barrier
	ds_read_b128 v[80:83], v234
	ds_read_b128 v[190:193], v234 offset:4608
	s_waitcnt lgkmcnt(1)
	v_mfma_f32_32x32x16_bf16 v[112:127], v[80:83], v[174:177], v[96:111]
	ds_read_b128 v[196:199], v234 offset:32
	v_exp_f32_e32 v216, v144
	v_exp_f32_e32 v217, v145
	v_exp_f32_e32 v144, v146
	v_exp_f32_e32 v145, v147
	s_waitcnt lgkmcnt(1)
	v_mfma_f32_32x32x16_bf16 v[80:95], v[190:193], v[174:177], v[96:111]
	ds_read_b128 v[242:245], v234 offset:4640
	v_exp_f32_e32 v146, v148
	v_exp_f32_e32 v147, v149
	s_waitcnt lgkmcnt(1)
	v_mfma_f32_32x32x16_bf16 v[112:127], v[196:199], v[170:173], v[112:127]
	ds_read_b128 v[190:193], v234 offset:64
	v_exp_f32_e32 v148, v150
	v_exp_f32_e32 v149, v151
	s_waitcnt lgkmcnt(1)
	v_mfma_f32_32x32x16_bf16 v[80:95], v[242:245], v[170:173], v[80:95]
	ds_read_b128 v[196:199], v234 offset:4672
	s_waitcnt vmcnt(0)
	ds_write_b128 v235, v[178:181] offset:9216
	ds_write_b128 v235, v[182:185] offset:18432
	ds_write_b128 v235, v[186:189] offset:27648
	v_cvt_pk_bf16_f32 v246, v216, v217
	v_cvt_pk_bf16_f32 v247, v144, v145
	v_cvt_pk_bf16_f32 v248, v146, v147
	v_cvt_pk_bf16_f32 v249, v148, v149
	s_waitcnt lgkmcnt(4)
	v_mfma_f32_32x32x16_bf16 v[112:127], v[190:193], v[166:169], v[112:127]
	ds_read_b128 v[242:245], v234 offset:96
	v_exp_f32_e32 v150, v152
	v_exp_f32_e32 v151, v153
	v_lshl_add_u64 v[152:153], v[206:207], 0, s[100:101]
	ds_read_b128 v[190:193], v234 offset:4704
	global_load_dwordx4 v[186:189], v[152:153], off
	global_load_dwordx4 v[178:181], v[208:209], off offset:384
	global_load_dwordx4 v[182:185], v[214:215], off offset:384
	s_waitcnt lgkmcnt(5)
	v_mfma_f32_32x32x16_bf16 v[80:95], v[196:199], v[166:169], v[80:95]
	v_exp_f32_e32 v210, v154
	v_exp_f32_e32 v211, v155
	s_waitcnt lgkmcnt(1)
	v_mfma_f32_32x32x16_bf16 v[112:127], v[242:245], v[162:165], v[112:127]
	ds_read_b128 v[152:155], v233 offset:36864
	v_exp_f32_e32 v212, v156
	v_exp_f32_e32 v213, v157
	s_waitcnt lgkmcnt(1)
	v_mfma_f32_32x32x16_bf16 v[80:95], v[190:193], v[162:165], v[80:95]
	ds_read_b128 v[196:199], v233 offset:41472
	v_exp_f32_e32 v214, v158
	v_exp_f32_e32 v215, v159
	s_waitcnt lgkmcnt(1)
	v_mfma_f32_32x32x16_bf16 v[0:15], v[152:155], v[246:249], v[0:15]
	ds_read_b128 v[156:159], v233 offset:46080
	v_cvt_pk_bf16_f32 v152, v150, v151
	v_cvt_pk_bf16_f32 v153, v210, v211
	v_cvt_pk_bf16_f32 v154, v212, v213
	v_cvt_pk_bf16_f32 v155, v214, v215
	v_exp_f32_e32 v242, v128
	v_exp_f32_e32 v243, v129
	s_waitcnt lgkmcnt(1)
	v_mfma_f32_32x32x16_bf16 v[48:63], v[196:199], v[246:249], v[48:63]
	ds_read_b128 v[190:193], v233 offset:50688
	v_exp_f32_e32 v196, v130
	v_exp_f32_e32 v197, v131
	s_waitcnt lgkmcnt(1)
	v_mfma_f32_32x32x16_bf16 v[32:47], v[156:159], v[246:249], v[32:47]
	ds_read_b128 v[128:131], v233 offset:36896
	v_exp_f32_e32 v198, v132
	v_exp_f32_e32 v199, v133
	s_waitcnt lgkmcnt(1)
	v_mfma_f32_32x32x16_bf16 v[16:31], v[190:193], v[246:249], v[16:31]
	ds_read_b128 v[156:159], v233 offset:41504
	v_exp_f32_e32 v244, v134
	v_exp_f32_e32 v245, v135
	s_waitcnt lgkmcnt(1)
	v_mfma_f32_32x32x16_bf16 v[0:15], v[128:131], v[152:155], v[0:15]
	ds_read_b128 v[132:135], v233 offset:46112
	v_cvt_pk_bf16_f32 v128, v242, v243
	v_cvt_pk_bf16_f32 v129, v196, v197
	v_cvt_pk_bf16_f32 v130, v198, v199
	v_cvt_pk_bf16_f32 v131, v244, v245
	s_waitcnt lgkmcnt(1)
	v_mfma_f32_32x32x16_bf16 v[48:63], v[156:159], v[152:155], v[48:63]
	ds_read_b128 v[190:193], v233 offset:50720
	v_exp_f32_e32 v246, v136
	v_exp_f32_e32 v247, v137
	s_waitcnt lgkmcnt(1)
	v_mfma_f32_32x32x16_bf16 v[32:47], v[132:135], v[152:155], v[32:47]
	ds_read_b128 v[156:159], v233 offset:36928
	v_exp_f32_e32 v248, v138
	v_exp_f32_e32 v249, v139
	s_waitcnt lgkmcnt(1)
	v_mfma_f32_32x32x16_bf16 v[16:31], v[190:193], v[152:155], v[16:31]
	ds_read_b128 v[132:135], v233 offset:41536
	v_exp_f32_e32 v190, v140
	v_exp_f32_e32 v191, v141
	s_waitcnt lgkmcnt(1)
	v_mfma_f32_32x32x16_bf16 v[0:15], v[156:159], v[128:131], v[0:15]
	ds_read_b128 v[136:139], v233 offset:46144
	v_exp_f32_e32 v156, v142
	v_exp_f32_e32 v157, v143
	v_cvt_pk_bf16_f32 v140, v246, v247
	v_cvt_pk_bf16_f32 v141, v248, v249
	v_cvt_pk_bf16_f32 v142, v190, v191
	v_cvt_pk_bf16_f32 v143, v156, v157
	s_waitcnt lgkmcnt(1)
	v_mfma_f32_32x32x16_bf16 v[48:63], v[132:135], v[128:131], v[48:63]
	ds_read_b128 v[152:155], v233 offset:50752
	v_add_f32_e64 v158, v212, v190
	v_add_f32_e64 v159, v213, v191
	v_add_f32_e64 v156, v214, v156
	v_add_f32_e64 v157, v215, v157
	v_pk_add_f32 v[190:191], v[210:211], v[248:249]
	v_pk_add_f32 v[150:151], v[150:151], v[246:247]
	v_pk_add_f32 v[146:147], v[146:147], v[198:199]
	v_pk_add_f32 v[192:193], v[216:217], v[242:243]
	v_pk_add_f32 v[148:149], v[148:149], v[244:245]
	v_pk_add_f32 v[144:145], v[144:145], v[196:197]
	s_waitcnt lgkmcnt(1)
	v_mfma_f32_32x32x16_bf16 v[32:47], v[136:139], v[128:131], v[32:47]
	v_add_f32_e64 v136, v144, v148
	v_add_f32_e64 v137, v145, v149
	v_add_f32_e64 v138, v192, v146
	v_add_f32_e64 v139, v193, v147
	v_add_f32_e64 v136, v190, v136
	v_add_f32_e64 v137, v191, v137
	v_pk_add_f32 v[138:139], v[150:151], v[138:139]
	v_pk_add_f32 v[136:137], v[156:157], v[136:137]
	v_pk_add_f32 v[138:139], v[158:159], v[138:139]
	ds_read_b128 v[132:135], v233 offset:36960
	v_pk_mov_b32 v[144:145], v[138:139], v[136:137] op_sel:[1,0]
	v_mov_b32_e32 v139, v137
	v_pk_add_f32 v[136:137], v[144:145], v[138:139]
	s_nop 0
	v_add_f32_e32 v136, v136, v137
	v_add_f32_e32 v216, v237, v136
	s_waitcnt lgkmcnt(1)
	v_mfma_f32_32x32x16_bf16 v[16:31], v[152:155], v[128:131], v[16:31]
	ds_read_b128 v[136:139], v233 offset:41568
	v_max3_f32 v128, v112, v113, v80
	v_max3_f32 v144, v114, v115, v81
	v_max3_f32 v145, v128, v82, v83
	s_waitcnt lgkmcnt(1)
	v_mfma_f32_32x32x16_bf16 v[0:15], v[132:135], v[140:143], v[0:15]
	ds_read_b128 v[128:131], v233 offset:46176
	v_max3_f32 v132, v145, v116, v117
	v_max3_f32 v133, v144, v118, v119
	v_max3_f32 v144, v132, v84, v85
	v_max3_f32 v145, v133, v86, v87
	s_waitcnt lgkmcnt(1)
	v_mfma_f32_32x32x16_bf16 v[48:63], v[136:139], v[140:143], v[48:63]
	ds_read_b128 v[132:135], v233 offset:50784
	v_max3_f32 v136, v144, v120, v121
	v_max3_f32 v137, v145, v122, v123
	v_max3_f32 v136, v136, v88, v89
	v_max3_f32 v137, v137, v90, v91
	s_waitcnt lgkmcnt(1)
	v_mfma_f32_32x32x16_bf16 v[32:47], v[128:131], v[140:143], v[32:47]
	v_max3_f32 v128, v136, v124, v125
	v_max3_f32 v129, v137, v126, v127
	v_max3_f32 v128, v128, v92, v93
	v_max3_f32 v129, v129, v94, v95
	v_max_f32_e32 v128, v128, v129
	v_mov_b32_e32 v129, v128
	s_waitcnt lgkmcnt(0)
	v_mfma_f32_32x32x16_bf16 v[16:31], v[132:135], v[140:143], v[16:31]
	v_permlane32_swap_b32_e32 v128, v129
	v_max_f32_e32 v128, v128, v129
	v_cmp_lt_f32_e32 vcc, s3, v128
	s_cbranch_vccz .LBB0_426
; __device__ __forceinline__ float fast_exp2(float x) { return __builtin_amdgcn_exp2f(x); }
; template <int DV, int PAR, bool KW = true, bool KL = true, bool VL = true>
; __device__ __forceinline__ void attn_iter_full(AttnState<DV>& S, int t, LAS unsigned char* lds) {
;     ...
;     if (__any(mx > 8.0f)) {
;         const float dl = fmaxf(mx, 0.f), alpha = fast_exp2(-dl);
;         S.mrun += dl; S.lsum *= alpha;
; #pragma unroll
;         for (int i = 0; i < 16; ++i) { sn0[i] -= dl; sn1[i] -= dl; S.negm[i] = -S.mrun; }
; #pragma unroll
;         for (int d = 0; d < NDB; ++d)
; #pragma unroll
;             for (int i = 0; i < 16; ++i) S.o[d][i] *= alpha;
;     }
	v_max_f32_e32 v64, v128, v128
	v_max_f32_e32 v65, 0, v64
	v_exp_f32_e64 v66, -v65
	v_add_f32_e32 v236, v236, v65
	v_xor_b32_e32 v64, 0x80000000, v236
	v_sub_f32_e32 v127, v127, v65
	v_mul_f32_e32 v216, v216, v66
	v_sub_f32_e32 v126, v126, v65
	v_sub_f32_e32 v125, v125, v65
	v_sub_f32_e32 v124, v124, v65
	v_sub_f32_e32 v123, v123, v65
	v_sub_f32_e32 v122, v122, v65
	v_sub_f32_e32 v121, v121, v65
	v_sub_f32_e32 v120, v120, v65
	v_sub_f32_e32 v119, v119, v65
	v_sub_f32_e32 v118, v118, v65
	v_sub_f32_e32 v117, v117, v65
	v_sub_f32_e32 v116, v116, v65
	v_sub_f32_e32 v115, v115, v65
	v_sub_f32_e32 v114, v114, v65
	v_sub_f32_e32 v113, v113, v65
	v_sub_f32_e32 v112, v112, v65
	v_sub_f32_e32 v95, v95, v65
	v_sub_f32_e32 v94, v94, v65
	v_sub_f32_e32 v93, v93, v65
	v_sub_f32_e32 v92, v92, v65
	v_sub_f32_e32 v91, v91, v65
	v_sub_f32_e32 v90, v90, v65
	v_sub_f32_e32 v89, v89, v65
	v_sub_f32_e32 v88, v88, v65
	v_sub_f32_e32 v87, v87, v65
	v_sub_f32_e32 v86, v86, v65
	v_sub_f32_e32 v85, v85, v65
	v_sub_f32_e32 v84, v84, v65
	v_sub_f32_e32 v83, v83, v65
	v_sub_f32_e32 v82, v82, v65
	v_sub_f32_e32 v81, v81, v65
	v_sub_f32_e32 v80, v80, v65
	v_pk_mul_f32 v[14:15], v[14:15], v[66:67] op_sel_hi:[1,0]
	v_pk_mul_f32 v[12:13], v[12:13], v[66:67] op_sel_hi:[1,0]
	v_pk_mul_f32 v[10:11], v[10:11], v[66:67] op_sel_hi:[1,0]
	v_pk_mul_f32 v[8:9], v[8:9], v[66:67] op_sel_hi:[1,0]
	v_pk_mul_f32 v[6:7], v[6:7], v[66:67] op_sel_hi:[1,0]
	v_pk_mul_f32 v[4:5], v[4:5], v[66:67] op_sel_hi:[1,0]
	v_pk_mul_f32 v[2:3], v[2:3], v[66:67] op_sel_hi:[1,0]
	v_pk_mul_f32 v[0:1], v[0:1], v[66:67] op_sel_hi:[1,0]
	v_pk_mul_f32 v[62:63], v[62:63], v[66:67] op_sel_hi:[1,0]
	v_pk_mul_f32 v[60:61], v[60:61], v[66:67] op_sel_hi:[1,0]
	v_pk_mul_f32 v[58:59], v[58:59], v[66:67] op_sel_hi:[1,0]
	v_pk_mul_f32 v[56:57], v[56:57], v[66:67] op_sel_hi:[1,0]
	v_pk_mul_f32 v[54:55], v[54:55], v[66:67] op_sel_hi:[1,0]
	v_pk_mul_f32 v[52:53], v[52:53], v[66:67] op_sel_hi:[1,0]
	v_pk_mul_f32 v[50:51], v[50:51], v[66:67] op_sel_hi:[1,0]
	v_pk_mul_f32 v[48:49], v[48:49], v[66:67] op_sel_hi:[1,0]
	v_pk_mul_f32 v[46:47], v[46:47], v[66:67] op_sel_hi:[1,0]
	v_pk_mul_f32 v[44:45], v[44:45], v[66:67] op_sel_hi:[1,0]
	v_pk_mul_f32 v[42:43], v[42:43], v[66:67] op_sel_hi:[1,0]
	v_pk_mul_f32 v[40:41], v[40:41], v[66:67] op_sel_hi:[1,0]
	v_pk_mul_f32 v[38:39], v[38:39], v[66:67] op_sel_hi:[1,0]
	v_pk_mul_f32 v[36:37], v[36:37], v[66:67] op_sel_hi:[1,0]
	v_pk_mul_f32 v[34:35], v[34:35], v[66:67] op_sel_hi:[1,0]
	v_pk_mul_f32 v[32:33], v[32:33], v[66:67] op_sel_hi:[1,0]
	v_pk_mul_f32 v[30:31], v[30:31], v[66:67] op_sel_hi:[1,0]
	v_pk_mul_f32 v[28:29], v[28:29], v[66:67] op_sel_hi:[1,0]
	v_pk_mul_f32 v[26:27], v[26:27], v[66:67] op_sel_hi:[1,0]
	v_pk_mul_f32 v[24:25], v[24:25], v[66:67] op_sel_hi:[1,0]
	v_pk_mul_f32 v[22:23], v[22:23], v[66:67] op_sel_hi:[1,0]
	v_pk_mul_f32 v[20:21], v[20:21], v[66:67] op_sel_hi:[1,0]
	v_pk_mul_f32 v[18:19], v[18:19], v[66:67] op_sel_hi:[1,0]
	v_pk_mul_f32 v[16:17], v[16:17], v[66:67] op_sel_hi:[1,0]
	v_mov_b32_e32 v65, v64
	v_mov_b32_e32 v66, v64
	v_mov_b32_e32 v67, v64
	v_mov_b32_e32 v68, v64
	v_mov_b32_e32 v69, v64
	v_mov_b32_e32 v70, v64
	v_mov_b32_e32 v71, v64
	v_mov_b32_e32 v72, v64
	v_mov_b32_e32 v73, v64
	v_mov_b32_e32 v74, v64
	v_mov_b32_e32 v75, v64
	v_mov_b32_e32 v76, v64
	v_mov_b32_e32 v77, v64
	v_mov_b32_e32 v78, v64
	v_mov_b32_e32 v79, v64
	v_mov_b32_e32 v96, v64
	v_mov_b32_e32 v97, v64
	v_mov_b32_e32 v98, v64
	v_mov_b32_e32 v99, v64
	v_mov_b32_e32 v100, v64
	v_mov_b32_e32 v101, v64
	v_mov_b32_e32 v102, v64
	v_mov_b32_e32 v103, v64
	v_mov_b32_e32 v104, v64
	v_mov_b32_e32 v105, v64
	v_mov_b32_e32 v106, v64
	v_mov_b32_e32 v107, v64
	v_mov_b32_e32 v108, v64
	v_mov_b32_e32 v109, v64
	v_mov_b32_e32 v110, v64
	v_mov_b32_e32 v111, v64
	s_branch .LBB0_426
